# scan_combine: wait for P prefetch only before its LDS store (not in the issuing step) plus L2 warm prefetch two segments ahead; on top of new P6c step loop and deferred raw-load packing
# speedup vs baseline: 1.0151x; 1.0151x over previous
; #define LAS __attribute__((address_space(3)))
; __device__ __forceinline__ void scan_combine(LAS unsigned char* lds, CArgsP a) {
;     ...
;     const int tid = threadIdx.x, h = blockIdx.x >> 3, rw = tid >> 6, v = (blockIdx.x & 7) * 8 + rw, kq = tid & 63;
;     const float* PM = (const float*)(a->ws + WS_PM); const float* UM = (const float*)(a->ws + WS_UM); float* SS = (float*)(a->ws + WS_SS);
;     LAS float* Sl = (LAS float*)lds;
;     LAS float* Pl = (LAS float*)(lds + 4096);
;     constexpr int GL = NSEG - 2;
;     float cur = SS[((size_t)(1 * 8 + h) * 64 + v) * 64 + kq];
;     f32x4 pa, pb;
;     float u1, u2;
;     {
;         const f32x4* P1 = (const f32x4*)(PM + (size_t)(1 * 8 + h) * 4096);
;         *(LAS f32x4*)(Pl + 1 * 4096 + 4 * tid) = P1[tid]; *(LAS f32x4*)(Pl + 1 * 4096 + 2048 + 4 * tid) = P1[512 + tid];
;         if (GL >= 2) { const f32x4* P2 = (const f32x4*)(PM + (size_t)(2 * 8 + h) * 4096);
;             *(LAS f32x4*)(Pl + 2 * 4096 + 4 * tid) = P2[tid]; *(LAS f32x4*)(Pl + 2 * 4096 + 2048 + 4 * tid) = P2[512 + tid]; }
;         u1 = UM[((size_t)(1 * 8 + h) * 64 + v) * 64 + kq];
;         u2 = GL >= 2 ? UM[((size_t)(2 * 8 + h) * 64 + v) * 64 + kq] : 0.f;
;     }
;     for (int g = 1; g <= GL; ++g) {
;         const bool pf = (g + 2 <= GL);
;         float u3 = 0.f;
;         if (pf) { const f32x4* Pn = (const f32x4*)(PM + (size_t)((g + 2) * 8 + h) * 4096); pa = Pn[tid]; pb = Pn[512 + tid]; u3 = UM[((size_t)((g + 2) * 8 + h) * 64 + v) * 64 + kq]; }
;         asm volatile("s_waitcnt lgkmcnt(0)\n\ts_barrier" ::: "memory");
;         const LAS float* Pg = Pl + (g % 3) * 4096 + kq;
;         float acc0 = u1, acc1 = 0.f, acc2 = 0.f, acc3 = 0.f;
;         const int curi = __builtin_bit_cast(int, cur);
; #pragma unroll
;         for (int k = 0; k < 64; k += 4) {
;             const float s0 = __builtin_bit_cast(float, __builtin_amdgcn_readlane(curi, k)), s1 = __builtin_bit_cast(float, __builtin_amdgcn_readlane(curi, k + 1));
;             const float s2 = __builtin_bit_cast(float, __builtin_amdgcn_readlane(curi, k + 2)), s3 = __builtin_bit_cast(float, __builtin_amdgcn_readlane(curi, k + 3));
;             acc0 += s0 * Pg[(k + 0) * 64]; acc1 += s1 * Pg[(k + 1) * 64]; acc2 += s2 * Pg[(k + 2) * 64]; acc3 += s3 * Pg[(k + 3) * 64];
.LBB0_1217:
	s_or_b64 exec, exec, s[8:9]
	s_mov_b64 s[20:21], s[92:93]
	s_cmp_gt_u32 s2, 63
	v_lshrrev_b32_e32 v50, 6, v164
	s_waitcnt lgkmcnt(0)
	s_barrier
	s_cbranch_scc1 .LBB0_1224
	s_load_dwordx2 s[4:5], s[20:21], 0xf8
	v_readlane_b32 s0, v250, 2
	s_lshr_b32 s3, s2, 3
	v_lshrrev_b32_e32 v0, 6, v164
	s_and_b32 s0, s0, 56
	v_add_u32_e32 v16, s0, v0
	s_waitcnt lgkmcnt(0)
	s_add_u32 s0, s4, 0xf600000
	s_addc_u32 s1, s5, 0
	s_add_u32 s6, s4, 0x300000
	s_addc_u32 s7, s5, 0
	s_add_u32 s4, s4, 0xbc00000
	s_addc_u32 s5, s5, 0
	s_or_b32 s8, s3, 8
	s_mov_b32 s9, 0
	s_lshl_b64 s[10:11], s[8:9], 12
	v_lshlrev_b32_e32 v8, 6, v16
	v_mov_b32_e32 v9, 0
	v_lshl_add_u64 v[0:1], v[8:9], 0, s[10:11]
	s_lshl_b64 s[10:11], s[8:9], 14
	s_add_u32 s10, s0, s10
	s_addc_u32 s11, s1, s11
	s_lshl_b32 s14, s3, 14
	v_or_b32_e32 v0, v0, v148
	v_lshlrev_b32_e32 v8, 4, v164
	s_or_b32 s3, s14, 0x40000
	v_lshlrev_b64 v[10:11], 2, v[0:1]
	v_lshl_add_u64 v[0:1], s[10:11], 0, v[8:9]
	s_movk_i32 s8, 0x2000
	s_add_u32 s12, s0, s3
	v_add_co_u32_e32 v6, vcc, s8, v0
	s_addc_u32 s13, s1, 0
	v_lshl_add_u64 v[4:5], s[4:5], 0, v[10:11]
	v_addc_co_u32_e32 v7, vcc, 0, v1, vcc
	v_lshl_add_u64 v[14:15], s[12:13], 0, v[8:9]
	global_load_dword v13, v[4:5], off
	global_load_dwordx4 v[0:3], v[6:7], off
	s_nop 0
	global_load_dwordx4 v[4:7], v8, s[10:11]
	global_load_dwordx4 v[20:23], v8, s[12:13]
	v_add_co_u32_e32 v14, vcc, s8, v14
	s_add_u32 s10, s6, s3
	v_add_u32_e32 v12, 0, v8
	v_addc_co_u32_e32 v15, vcc, 0, v15, vcc
	s_addc_u32 s11, s7, 0
	v_lshlrev_b32_e32 v8, 8, v16
	global_load_dwordx4 v[24:27], v[14:15], off
	v_lshl_add_u64 v[10:11], s[6:7], 0, v[10:11]
	v_lshl_add_u64 v[14:15], s[10:11], 0, v[8:9]
	v_mov_b32_e32 v101, v9
	v_lshl_add_u64 v[16:17], v[14:15], 0, v[100:101]
	global_load_dword v18, v[10:11], off
	global_load_dword v14, v[16:17], off
	v_add_u32_e32 v16, 0x200, v164
	v_lshl_add_u64 v[10:11], s[6:7], 0, v[8:9]
	v_lshl_add_u64 v[28:29], s[4:5], 0, v[8:9]
	s_mov_b32 s3, 3
	v_lshl_add_u32 v15, v148, 2, 0
	s_add_i32 s8, s14, 0x40000
	s_add_i32 s15, s14, 0x7c0000
	v_lshl_add_u64 v[8:9], v[10:11], 0, v[100:101]
	v_lshl_add_u64 v[10:11], v[28:29], 0, v[100:101]
	v_lshlrev_b32_e32 v16, 4, v16
	v_lshlrev_b32_e32 v17, 4, v164
	s_waitcnt vmcnt(4)
	ds_write_b128 v12, v[4:7] offset:20480
	ds_write_b128 v12, v[0:3] offset:28672
	s_waitcnt vmcnt(3)
	ds_write_b128 v12, v[20:23] offset:36864
	s_waitcnt vmcnt(2)
	ds_write_b128 v12, v[24:27] offset:45056
	s_waitcnt vmcnt(0)
	s_branch .LBB0_1220
.LBB0_1219:
	s_add_i32 s3, s3, 1
	s_add_i32 s8, s8, 0x20000
	s_cmpk_lg_i32 s3, 0x41
	s_waitcnt vmcnt(3)
	v_mov_b32_e32 v18, v14
	v_mov_b32_e32 v14, v19
	s_cbranch_scc0 .LBB0_1224
.LBB0_1220:
	s_add_i32 s4, s3, -2
	s_cmp_lt_u32 s4, 61
	s_cselect_b64 s[10:11], -1, 0
	s_cmp_gt_u32 s4, 60
	v_mov_b32_e32 v19, 0
	s_cbranch_scc1 .LBB0_1222
	s_add_i32 s6, s8, 0x20000
	s_mov_b32 s7, s9
	v_lshl_add_u64 v[20:21], v[8:9], 0, s[6:7]
	s_add_u32 s6, s0, s6
	s_addc_u32 s7, s1, 0
	global_load_dwordx4 v[0:3], v17, s[6:7]
	global_load_dwordx4 v[4:7], v16, s[6:7]
	global_load_dword v19, v[20:21], off
	s_add_i32 s12, s8, 0x60000
	s_min_u32 s12, s12, s15
	s_add_u32 s12, s0, s12
	s_addc_u32 s13, s1, 0
	global_load_dwordx4 v[32:35], v17, s[12:13]
	global_load_dwordx4 v[36:39], v16, s[12:13]
.LBB0_1222:
	s_mul_i32 s5, s4, 0xab
	s_bfe_u32 s5, s5, 0x70009
	s_mul_i32 s5, s5, 3
	s_sub_i32 s4, s4, s5
	s_and_b32 s4, s4, 0xff
	s_waitcnt lgkmcnt(0)
	s_barrier
	v_lshl_add_u32 v28, s4, 14, v15
	ds_read2st64_b32 v[20:21], v28 offset0:16 offset1:17
	ds_read2st64_b32 v[22:23], v28 offset0:18 offset1:19
	ds_read2st64_b32 v[24:25], v28 offset0:20 offset1:21
	ds_read2st64_b32 v[26:27], v28 offset0:22 offset1:23
	v_readlane_b32 s4, v13, 0
	v_readlane_b32 s5, v13, 1
	v_readlane_b32 s6, v13, 2
	v_readlane_b32 s7, v13, 3
	s_waitcnt lgkmcnt(3)
	v_fmac_f32_e32 v18, s4, v20
	v_fma_f32 v29, v21, s5, 0
	s_waitcnt lgkmcnt(2)
	v_fma_f32 v30, v22, s6, 0
	v_fma_f32 v31, v23, s7, 0
	v_readlane_b32 s4, v13, 4
	v_readlane_b32 s5, v13, 5
	v_readlane_b32 s6, v13, 6
	v_readlane_b32 s7, v13, 7
	ds_read2st64_b32 v[20:21], v28 offset0:24 offset1:25
	s_waitcnt lgkmcnt(2)
	v_fmac_f32_e32 v18, s4, v24
	v_fmac_f32_e32 v29, s5, v25
	s_waitcnt lgkmcnt(1)
	v_fmac_f32_e32 v30, s6, v26
	v_fmac_f32_e32 v31, s7, v27
	ds_read2st64_b32 v[22:23], v28 offset0:26 offset1:27
	ds_read2st64_b32 v[24:25], v28 offset0:28 offset1:29
	ds_read2st64_b32 v[26:27], v28 offset0:30 offset1:31
	v_readlane_b32 s4, v13, 8
	v_readlane_b32 s5, v13, 9
	v_readlane_b32 s6, v13, 10
	v_readlane_b32 s7, v13, 11
	s_waitcnt lgkmcnt(3)
	v_fmac_f32_e32 v18, s4, v20
	v_fmac_f32_e32 v29, s5, v21
	s_waitcnt lgkmcnt(2)
	v_fmac_f32_e32 v30, s6, v22
	v_fmac_f32_e32 v31, s7, v23
	v_readlane_b32 s4, v13, 12
	v_readlane_b32 s5, v13, 13
	v_readlane_b32 s6, v13, 14
	v_readlane_b32 s7, v13, 15
	ds_read2st64_b32 v[20:21], v28 offset0:32 offset1:33
	s_waitcnt lgkmcnt(2)
	v_fmac_f32_e32 v18, s4, v24
	v_fmac_f32_e32 v29, s5, v25
	s_waitcnt lgkmcnt(1)
	v_fmac_f32_e32 v30, s6, v26
	v_fmac_f32_e32 v31, s7, v27
	ds_read2st64_b32 v[22:23], v28 offset0:34 offset1:35
	ds_read2st64_b32 v[24:25], v28 offset0:36 offset1:37
	ds_read2st64_b32 v[26:27], v28 offset0:38 offset1:39
	v_readlane_b32 s4, v13, 16
	v_readlane_b32 s5, v13, 17
	v_readlane_b32 s6, v13, 18
	v_readlane_b32 s7, v13, 19
	s_waitcnt lgkmcnt(3)
	v_fmac_f32_e32 v18, s4, v20
	v_fmac_f32_e32 v29, s5, v21
	s_waitcnt lgkmcnt(2)
	v_fmac_f32_e32 v30, s6, v22
	v_fmac_f32_e32 v31, s7, v23
	v_readlane_b32 s4, v13, 20
	v_readlane_b32 s5, v13, 21
	v_readlane_b32 s6, v13, 22
	v_readlane_b32 s7, v13, 23
	ds_read2st64_b32 v[20:21], v28 offset0:40 offset1:41
	s_waitcnt lgkmcnt(2)
; #define LAS __attribute__((address_space(3)))
; __device__ __forceinline__ CArgsP get_args() { CArgsP p = (CArgsP)__builtin_amdgcn_kernarg_segment_ptr(); asm volatile("" : "+s"(p)); return p; }
; #define PH(k) for (int r_ = 0, n_ = probe_reps(k); r_ < n_; ++r_)
; __device__ __forceinline__ void scan_combine(LAS unsigned char* lds, CArgsP a) {
;     ...
;         for (int k = 0; k < 64; k += 4) {
;             const float s0 = __builtin_bit_cast(float, __builtin_amdgcn_readlane(curi, k)), s1 = __builtin_bit_cast(float, __builtin_amdgcn_readlane(curi, k + 1));
;             const float s2 = __builtin_bit_cast(float, __builtin_amdgcn_readlane(curi, k + 2)), s3 = __builtin_bit_cast(float, __builtin_amdgcn_readlane(curi, k + 3));
;             acc0 += s0 * Pg[(k + 0) * 64]; acc1 += s1 * Pg[(k + 1) * 64]; acc2 += s2 * Pg[(k + 2) * 64]; acc3 += s3 * Pg[(k + 3) * 64];
;         }
;         cur = (acc0 + acc1) + (acc2 + acc3);
;         SS[((size_t)((g + 1) * 8 + h) * 64 + v) * 64 + kq] = cur;
;         if (pf) { LAS float* dst = Pl + ((g + 2) % 3) * 4096; *(LAS f32x4*)(dst + 4 * tid) = pa; *(LAS f32x4*)(dst + 2048 + 4 * tid) = pb; }
;         u1 = u2; u2 = u3;
;     }
; __global__ void __launch_bounds__(512, 2) mega_fwd(Args a_unused) {
;     ...
;     PH(7) { CArgsP a = get_args(); if (bx < 64 || G <= 64) scan_combine(lds, a); __syncthreads(); if (G != 256 && (bx >= 64 || G <= 64)) convert_weights(a, lds, wave, lane, 1, G <= 64 ? bx : bx - 64, G <= 64 ? G : G - 64); if (G == 256 && bx >= 64 && bx < 192) attn_sample_unit(lds, a, (bx - 64) >> 3, (bx - 64) & 7);
	v_fmac_f32_e32 v18, s4, v24
	v_fmac_f32_e32 v29, s5, v25
	s_waitcnt lgkmcnt(1)
	v_fmac_f32_e32 v30, s6, v26
	v_fmac_f32_e32 v31, s7, v27
	ds_read2st64_b32 v[22:23], v28 offset0:42 offset1:43
	ds_read2st64_b32 v[24:25], v28 offset0:44 offset1:45
	ds_read2st64_b32 v[26:27], v28 offset0:46 offset1:47
	v_readlane_b32 s4, v13, 24
	v_readlane_b32 s5, v13, 25
	v_readlane_b32 s6, v13, 26
	v_readlane_b32 s7, v13, 27
	s_waitcnt lgkmcnt(3)
	v_fmac_f32_e32 v18, s4, v20
	v_fmac_f32_e32 v29, s5, v21
	s_waitcnt lgkmcnt(2)
	v_fmac_f32_e32 v30, s6, v22
	v_fmac_f32_e32 v31, s7, v23
	v_readlane_b32 s4, v13, 28
	v_readlane_b32 s5, v13, 29
	v_readlane_b32 s6, v13, 30
	v_readlane_b32 s7, v13, 31
	ds_read2st64_b32 v[20:21], v28 offset0:48 offset1:49
	s_waitcnt lgkmcnt(2)
	v_fmac_f32_e32 v18, s4, v24
	v_fmac_f32_e32 v29, s5, v25
	s_waitcnt lgkmcnt(1)
	v_fmac_f32_e32 v30, s6, v26
	v_fmac_f32_e32 v31, s7, v27
	ds_read2st64_b32 v[22:23], v28 offset0:50 offset1:51
	ds_read2st64_b32 v[24:25], v28 offset0:52 offset1:53
	ds_read2st64_b32 v[26:27], v28 offset0:54 offset1:55
	v_readlane_b32 s4, v13, 32
	v_readlane_b32 s5, v13, 33
	v_readlane_b32 s6, v13, 34
	v_readlane_b32 s7, v13, 35
	s_waitcnt lgkmcnt(3)
	v_fmac_f32_e32 v18, s4, v20
	v_fmac_f32_e32 v29, s5, v21
	s_waitcnt lgkmcnt(2)
	v_fmac_f32_e32 v30, s6, v22
	v_fmac_f32_e32 v31, s7, v23
	v_readlane_b32 s4, v13, 36
	v_readlane_b32 s5, v13, 37
	v_readlane_b32 s6, v13, 38
	v_readlane_b32 s7, v13, 39
	ds_read2st64_b32 v[20:21], v28 offset0:56 offset1:57
	s_waitcnt lgkmcnt(2)
	v_fmac_f32_e32 v18, s4, v24
	v_fmac_f32_e32 v29, s5, v25
	s_waitcnt lgkmcnt(1)
	v_fmac_f32_e32 v30, s6, v26
	v_fmac_f32_e32 v31, s7, v27
	ds_read2st64_b32 v[22:23], v28 offset0:58 offset1:59
	ds_read2st64_b32 v[24:25], v28 offset0:60 offset1:61
	ds_read2st64_b32 v[26:27], v28 offset0:62 offset1:63
	v_readlane_b32 s4, v13, 40
	v_readlane_b32 s5, v13, 41
	v_readlane_b32 s6, v13, 42
	v_readlane_b32 s7, v13, 43
	s_waitcnt lgkmcnt(3)
	v_fmac_f32_e32 v18, s4, v20
	v_fmac_f32_e32 v29, s5, v21
	s_waitcnt lgkmcnt(2)
	v_fmac_f32_e32 v30, s6, v22
	v_fmac_f32_e32 v31, s7, v23
	v_readlane_b32 s4, v13, 44
	v_readlane_b32 s5, v13, 45
	v_readlane_b32 s6, v13, 46
	v_readlane_b32 s7, v13, 47
	ds_read2st64_b32 v[20:21], v28 offset0:64 offset1:65
	s_waitcnt lgkmcnt(2)
	v_fmac_f32_e32 v18, s4, v24
	v_fmac_f32_e32 v29, s5, v25
	s_waitcnt lgkmcnt(1)
	v_fmac_f32_e32 v30, s6, v26
	v_fmac_f32_e32 v31, s7, v27
	ds_read2st64_b32 v[22:23], v28 offset0:66 offset1:67
	ds_read2st64_b32 v[24:25], v28 offset0:68 offset1:69
	ds_read2st64_b32 v[26:27], v28 offset0:70 offset1:71
	v_readlane_b32 s4, v13, 48
	v_readlane_b32 s5, v13, 49
	v_readlane_b32 s6, v13, 50
	v_readlane_b32 s7, v13, 51
	s_waitcnt lgkmcnt(3)
	v_fmac_f32_e32 v18, s4, v20
	v_fmac_f32_e32 v29, s5, v21
	s_waitcnt lgkmcnt(2)
	v_fmac_f32_e32 v30, s6, v22
	v_fmac_f32_e32 v31, s7, v23
	v_readlane_b32 s4, v13, 52
	v_readlane_b32 s5, v13, 53
	v_readlane_b32 s6, v13, 54
	v_readlane_b32 s7, v13, 55
	ds_read2st64_b32 v[20:21], v28 offset0:72 offset1:73
	s_waitcnt lgkmcnt(2)
	v_fmac_f32_e32 v18, s4, v24
	v_fmac_f32_e32 v29, s5, v25
	s_waitcnt lgkmcnt(1)
	v_fmac_f32_e32 v30, s6, v26
	v_fmac_f32_e32 v31, s7, v27
	ds_read2st64_b32 v[22:23], v28 offset0:74 offset1:75
	ds_read2st64_b32 v[24:25], v28 offset0:76 offset1:77
	ds_read2st64_b32 v[26:27], v28 offset0:78 offset1:79
	v_readlane_b32 s4, v13, 56
	v_readlane_b32 s5, v13, 57
	v_readlane_b32 s6, v13, 58
	v_readlane_b32 s7, v13, 59
	s_waitcnt lgkmcnt(3)
	v_fmac_f32_e32 v18, s4, v20
	v_fmac_f32_e32 v29, s5, v21
	s_waitcnt lgkmcnt(2)
	v_fmac_f32_e32 v30, s6, v22
	v_fmac_f32_e32 v31, s7, v23
	v_readlane_b32 s4, v13, 60
	v_readlane_b32 s5, v13, 61
	v_readlane_b32 s6, v13, 62
	v_readlane_b32 s7, v13, 63
	s_waitcnt lgkmcnt(1)
	v_fmac_f32_e32 v18, s4, v24
	v_fmac_f32_e32 v29, s5, v25
	s_waitcnt lgkmcnt(0)
	v_fmac_f32_e32 v30, s6, v26
	v_fmac_f32_e32 v31, s7, v27
	v_add_f32_e32 v13, v18, v29
	v_add_f32_e32 v18, v30, v31
	v_add_f32_e32 v13, v13, v18
	v_lshl_add_u64 v[20:21], v[10:11], 0, s[8:9]
	s_andn2_b64 vcc, exec, s[10:11]
	global_store_dword v[20:21], v13, off
	s_cbranch_vccnz .LBB0_1219
	s_mul_i32 s4, s3, 0xab
	s_bfe_u32 s4, s4, 0x70009
	s_mul_i32 s4, s4, 3
	s_sub_i32 s4, s3, s4
	s_and_b32 s4, s4, 0xff
	v_lshl_add_u32 v18, s4, 14, v12
	s_waitcnt vmcnt(4)
	ds_write_b128 v18, v[0:3] offset:4096
	ds_write_b128 v18, v[4:7] offset:12288
	s_branch .LBB0_1219
.LBB0_1224:
	s_waitcnt vmcnt(0)
	s_cmpk_lt_i32 s60, 0x41
	s_cselect_b64 s[8:9], -1, 0
	s_xor_b64 s[22:23], s[66:67], -1
	s_cmp_gt_i32 s2, 63
	s_cselect_b64 s[0:1], -1, 0
	s_or_b64 s[0:1], s[0:1], s[8:9]
	s_and_b64 s[0:1], s[0:1], s[22:23]
	s_andn2_b64 vcc, exec, s[0:1]
	s_sub_i32 s0, s2, 64
	s_waitcnt lgkmcnt(0)
	s_barrier
	s_cbranch_vccnz .LBB0_1241
	s_and_b64 s[4:5], s[8:9], exec
	s_cselect_b32 s1, s2, s0
	s_cmpk_gt_i32 s1, 0x24f
	s_cbranch_scc1 .LBB0_1240
	s_load_dwordx2 s[6:7], s[20:21], 0xf8
	s_sub_i32 s3, s60, 64
	s_and_b64 s[4:5], s[8:9], exec
	s_cselect_b32 s3, s60, s3
	v_readlane_b32 s5, v250, 3
	s_waitcnt lgkmcnt(0)
	s_add_u32 s12, s6, 0x1b00000
	s_addc_u32 s13, s7, 0
	s_lshl_b32 s4, s79, 3
	s_and_b32 s5, s5, 0xc0
	v_or_b32_e32 v53, s5, v148
	s_or_b32 s5, s4, 24
	s_and_b32 s9, s4, 0x1fffffe0
	s_mul_i32 s11, s5, 0x410
	s_or_b32 s5, s4, 1
	s_add_u32 s16, s6, 0x2800000
	s_addc_u32 s17, s7, 0
	s_add_u32 s18, s6, 0x1d00000
	v_lshrrev_b32_e32 v2, 5, v148
	v_and_b32_e32 v0, 28, v165
	v_lshl_add_u32 v52, v165, 2, 0
	s_mul_i32 s8, s79, 0x2080
	v_lshl_add_u32 v1, v53, 2, 0
	s_mul_i32 s10, s9, 0x410
	s_addc_u32 s19, s7, 0
	v_mul_u32_u24_e32 v2, 0xb00, v2
	s_movk_i32 s6, 0x60
	s_lshl_b32 s14, s1, 4
	v_and_b32_e32 v51, 0xe0, v165
	s_mov_b32 s15, 0
	v_mov_b32_e32 v49, 0
	s_mulk_i32 s5, 0x410
	v_and_or_b32 v54, v165, s6, v2
	s_lshl_b32 s6, s1, 6
	s_lshl_b32 s7, s3, 6
	s_add_i32 s24, s14, 0x7fffdf00
	s_lshl_b32 s25, s3, 4
	v_add_u32_e32 v55, s8, v52
	v_add_u32_e32 v56, s10, v1
	s_movk_i32 s26, 0x7fff
	s_mov_b32 s27, 0xffff0000
	v_add_u32_e32 v57, s11, v1
	s_lshl_b32 s14, s9, 1
	v_lshlrev_b32_e32 v48, 2, v0
	v_mov_b32_e32 v58, 0x5800
	s_branch .LBB0_1230

; #define LAS __attribute__((address_space(3)))
; template <int CTRL> __device__ __forceinline__ float dpp_f(float x) { return __builtin_bit_cast(float, __builtin_amdgcn_mov_dpp(__builtin_bit_cast(int, x), CTRL, 0xf, 0xf, true)); }
; __device__ __forceinline__ float red8(float d) { d += dpp_f<0xB1>(d); d += dpp_f<0x4E>(d); d += dpp_f<0x141>(d); return d; }
; __device__ __forceinline__ void upd8(V8& S, const V8& w, const V8& b, const V8& k, float sa, float vv) {
;     const f32x2 sa2 = {sa, sa}, vv2 = {vv, vv};
; #pragma unroll
;     for (int i = 0; i < 4; ++i) { f32x2 t = vv2 * k.p[i]; t = sa2 * b.p[i] + t; S.p[i] = S.p[i] * w.p[i] + t; }
; template <int MODE>
; __device__ __forceinline__ void scan_pair(LAS unsigned char* lds, CArgsP a, const ScanUnit u, int nch) {
;     ...
;         for (int t = 0; t < 16; ++t) {
;             const LAS float* p = cb + t * 64 + 8 * ks;
;             const V8 w = ld8(p), kk = ld8(p + 1024), bb = ld8(p + 2048), kv = ld8(p + 3072);
;             const float va = cb[(5 * 16 + t) * 64 + vr0], vb = cb[(5 * 16 + t) * 64 + vr1];
;             float da = dot8(Sa, kk), db = dot8(Sb, kk);
;             da = red8(da); db = red8(db);
;             upd8(Sa, w, bb, kv, -da, va); upd8(Sb, w, bb, kv, -db, vb);
;             if (MODE == 1) {
;                 float pa = dot8(Pa, kk), pb = dot8(Pb, kk);
;                 pa = red8(pa); pb = red8(pb);
;                 updp8(Pa, w, bb, -pa); updp8(Pb, w, bb, -pb);
;             } else {
;                 const V8 rr = ld8(p + 4096);
;                 float ya = dot8(Sa, rr), yb = dot8(Sb, rr);
;                 ya = red8(ya); yb = red8(yb);
;                 if (ks == 0) { Y[t * 64 + vr0] = ya; Y[t * 64 + vr1] = yb; }
;             }
.LBB0_1537:
	v_cndmask_b32_e64 v40, 0, 1, s[38:39]
	v_mul_lo_u32 v40, v40, s3
	v_add_u32_e32 v166, v54, v40
	v_add_u32_e32 v167, v53, v40
	v_add_u32_e32 v168, 0xe000, v52
	ds_read_b128 v[208:211], v166 offset:0
	ds_read_b128 v[212:215], v166 offset:16
	ds_read_b128 v[216:219], v166 offset:4096
	ds_read_b128 v[220:223], v166 offset:4112
	ds_read_b128 v[224:227], v166 offset:8192
	ds_read_b128 v[228:231], v166 offset:8208
	ds_read_b128 v[232:235], v166 offset:12288
	ds_read_b128 v[236:239], v166 offset:12304
	ds_read2_b32 v[248:249], v167 offset0:0 offset1:8
	ds_read_b128 v[104:107], v166 offset:256
	ds_read_b128 v[108:111], v166 offset:272
	ds_read_b128 v[112:115], v166 offset:4352
	ds_read_b128 v[116:119], v166 offset:4368
	ds_read_b128 v[120:123], v166 offset:8448
	ds_read_b128 v[124:127], v166 offset:8464
	ds_read_b128 v[128:131], v166 offset:12544
	ds_read_b128 v[132:135], v166 offset:12560
	ds_read_b128 v[136:139], v166 offset:16384
	ds_read_b128 v[140:143], v166 offset:16400
	ds_read2_b32 v[98:99], v167 offset0:64 offset1:72
	s_waitcnt lgkmcnt(11)
	v_pk_mul_f32 v[40:41], v[12:13], v[216:217]
	v_pk_mul_f32 v[42:43], v[4:5], v[216:217]
	v_pk_fma_f32 v[40:41], v[14:15], v[218:219], v[40:41]
	v_pk_fma_f32 v[42:43], v[6:7], v[218:219], v[42:43]
	v_pk_fma_f32 v[40:41], v[8:9], v[220:221], v[40:41]
	v_pk_fma_f32 v[42:43], v[0:1], v[220:221], v[42:43]
	v_pk_fma_f32 v[40:41], v[10:11], v[222:223], v[40:41]
	v_pk_fma_f32 v[42:43], v[2:3], v[222:223], v[42:43]
	v_add_f32_e32 v40, v40, v41
	v_add_f32_e32 v42, v42, v43
	v_pk_mul_f32 v[88:89], v[232:233], v[248:249] op_sel_hi:[1,0]
	v_pk_mul_f32 v[90:91], v[232:233], v[248:249] op_sel:[0,1] op_sel_hi:[1,1]
	v_pk_mul_f32 v[92:93], v[234:235], v[248:249] op_sel_hi:[1,0]
	v_pk_mul_f32 v[94:95], v[234:235], v[248:249] op_sel:[0,1] op_sel_hi:[1,1]
	v_add_f32_dpp v40, v40, v40 quad_perm:[1,0,3,2] row_mask:0xf bank_mask:0xf bound_ctrl:1
	v_add_f32_dpp v42, v42, v42 quad_perm:[1,0,3,2] row_mask:0xf bank_mask:0xf bound_ctrl:1
	v_pk_fma_f32 v[12:13], v[12:13], v[208:209], v[88:89]
	v_pk_fma_f32 v[4:5], v[4:5], v[208:209], v[90:91]
	v_pk_fma_f32 v[14:15], v[14:15], v[210:211], v[92:93]
	v_pk_fma_f32 v[6:7], v[6:7], v[210:211], v[94:95]
	v_add_f32_dpp v40, v40, v40 quad_perm:[2,3,0,1] row_mask:0xf bank_mask:0xf bound_ctrl:1
	v_add_f32_dpp v42, v42, v42 quad_perm:[2,3,0,1] row_mask:0xf bank_mask:0xf bound_ctrl:1
	v_pk_mul_f32 v[88:89], v[236:237], v[248:249] op_sel_hi:[1,0]
	v_pk_mul_f32 v[90:91], v[236:237], v[248:249] op_sel:[0,1] op_sel_hi:[1,1]
	v_pk_mul_f32 v[92:93], v[238:239], v[248:249] op_sel_hi:[1,0]
	v_pk_mul_f32 v[94:95], v[238:239], v[248:249] op_sel:[0,1] op_sel_hi:[1,1]
	v_add_f32_dpp v40, v40, v40 row_half_mirror row_mask:0xf bank_mask:0xf bound_ctrl:1
	v_add_f32_dpp v42, v42, v42 row_half_mirror row_mask:0xf bank_mask:0xf bound_ctrl:1
	v_pk_fma_f32 v[8:9], v[8:9], v[212:213], v[88:89]
	v_pk_fma_f32 v[0:1], v[0:1], v[212:213], v[90:91]
	v_pk_fma_f32 v[10:11], v[10:11], v[214:215], v[92:93]
	v_pk_fma_f32 v[2:3], v[2:3], v[214:215], v[94:95]
	v_pk_fma_f32 v[12:13], v[224:225], v[40:41], v[12:13] op_sel_hi:[1,0,1] neg_lo:[0,1,0] neg_hi:[0,1,0]
	v_pk_fma_f32 v[4:5], v[224:225], v[42:43], v[4:5] op_sel_hi:[1,0,1] neg_lo:[0,1,0] neg_hi:[0,1,0]
	v_pk_fma_f32 v[14:15], v[226:227], v[40:41], v[14:15] op_sel_hi:[1,0,1] neg_lo:[0,1,0] neg_hi:[0,1,0]
	v_pk_fma_f32 v[6:7], v[226:227], v[42:43], v[6:7] op_sel_hi:[1,0,1] neg_lo:[0,1,0] neg_hi:[0,1,0]
	v_pk_fma_f32 v[8:9], v[228:229], v[40:41], v[8:9] op_sel_hi:[1,0,1] neg_lo:[0,1,0] neg_hi:[0,1,0]
	v_pk_fma_f32 v[0:1], v[228:229], v[42:43], v[0:1] op_sel_hi:[1,0,1] neg_lo:[0,1,0] neg_hi:[0,1,0]
	v_pk_fma_f32 v[10:11], v[230:231], v[40:41], v[10:11] op_sel_hi:[1,0,1] neg_lo:[0,1,0] neg_hi:[0,1,0]
	v_pk_fma_f32 v[2:3], v[230:231], v[42:43], v[2:3] op_sel_hi:[1,0,1] neg_lo:[0,1,0] neg_hi:[0,1,0]
	ds_read_b128 v[208:211], v166 offset:512
	ds_read_b128 v[212:215], v166 offset:528
	ds_read_b128 v[216:219], v166 offset:4608
	ds_read_b128 v[220:223], v166 offset:4624
	ds_read_b128 v[224:227], v166 offset:8704
	ds_read_b128 v[228:231], v166 offset:8720
	ds_read_b128 v[232:235], v166 offset:12800
	ds_read_b128 v[236:239], v166 offset:12816
	ds_read_b128 v[240:243], v166 offset:16640
	ds_read_b128 v[244:247], v166 offset:16656
	ds_read2_b32 v[248:249], v167 offset0:128 offset1:136
	s_waitcnt lgkmcnt(11)
; #define LAS __attribute__((address_space(3)))
; template <int CTRL> __device__ __forceinline__ float dpp_f(float x) { return __builtin_bit_cast(float, __builtin_amdgcn_mov_dpp(__builtin_bit_cast(int, x), CTRL, 0xf, 0xf, true)); }
; __device__ __forceinline__ float red8(float d) { d += dpp_f<0xB1>(d); d += dpp_f<0x4E>(d); d += dpp_f<0x141>(d); return d; }
; __device__ __forceinline__ void upd8(V8& S, const V8& w, const V8& b, const V8& k, float sa, float vv) {
;     const f32x2 sa2 = {sa, sa}, vv2 = {vv, vv};
; #pragma unroll
;     for (int i = 0; i < 4; ++i) { f32x2 t = vv2 * k.p[i]; t = sa2 * b.p[i] + t; S.p[i] = S.p[i] * w.p[i] + t; }
; template <int MODE>
; __device__ __forceinline__ void scan_pair(LAS unsigned char* lds, CArgsP a, const ScanUnit u, int nch) {
;     ...
;         for (int t = 0; t < 16; ++t) {
;             const LAS float* p = cb + t * 64 + 8 * ks;
;             const V8 w = ld8(p), kk = ld8(p + 1024), bb = ld8(p + 2048), kv = ld8(p + 3072);
;             const float va = cb[(5 * 16 + t) * 64 + vr0], vb = cb[(5 * 16 + t) * 64 + vr1];
;             float da = dot8(Sa, kk), db = dot8(Sb, kk);
;             da = red8(da); db = red8(db);
;             upd8(Sa, w, bb, kv, -da, va); upd8(Sb, w, bb, kv, -db, vb);
;             if (MODE == 1) {
;                 float pa = dot8(Pa, kk), pb = dot8(Pb, kk);
;                 pa = red8(pa); pb = red8(pb);
;                 updp8(Pa, w, bb, -pa); updp8(Pb, w, bb, -pb);
;             } else {
;                 const V8 rr = ld8(p + 4096);
;                 float ya = dot8(Sa, rr), yb = dot8(Sb, rr);
;                 ya = red8(ya); yb = red8(yb);
;                 if (ks == 0) { Y[t * 64 + vr0] = ya; Y[t * 64 + vr1] = yb; }
;             }
	v_pk_mul_f32 v[40:41], v[12:13], v[112:113]
	v_pk_mul_f32 v[42:43], v[4:5], v[112:113]
	v_pk_mul_f32 v[44:45], v[12:13], v[136:137]
	v_pk_mul_f32 v[46:47], v[4:5], v[136:137]
	v_pk_fma_f32 v[40:41], v[14:15], v[114:115], v[40:41]
	v_pk_fma_f32 v[42:43], v[6:7], v[114:115], v[42:43]
	v_pk_fma_f32 v[44:45], v[14:15], v[138:139], v[44:45]
	v_pk_fma_f32 v[46:47], v[6:7], v[138:139], v[46:47]
	v_pk_fma_f32 v[40:41], v[8:9], v[116:117], v[40:41]
	v_pk_fma_f32 v[42:43], v[0:1], v[116:117], v[42:43]
	v_pk_fma_f32 v[44:45], v[8:9], v[140:141], v[44:45]
	v_pk_fma_f32 v[46:47], v[0:1], v[140:141], v[46:47]
	v_pk_fma_f32 v[40:41], v[10:11], v[118:119], v[40:41]
	v_pk_fma_f32 v[42:43], v[2:3], v[118:119], v[42:43]
	v_pk_fma_f32 v[44:45], v[10:11], v[142:143], v[44:45]
	v_pk_fma_f32 v[46:47], v[2:3], v[142:143], v[46:47]
	v_add_f32_e32 v40, v40, v41
	v_add_f32_e32 v42, v42, v43
	v_add_f32_e32 v44, v44, v45
	v_add_f32_e32 v46, v46, v47
	v_pk_mul_f32 v[88:89], v[128:129], v[98:99] op_sel_hi:[1,0]
	v_pk_mul_f32 v[90:91], v[128:129], v[98:99] op_sel:[0,1] op_sel_hi:[1,1]
	v_pk_mul_f32 v[92:93], v[130:131], v[98:99] op_sel_hi:[1,0]
	v_pk_mul_f32 v[94:95], v[130:131], v[98:99] op_sel:[0,1] op_sel_hi:[1,1]
	v_add_f32_dpp v40, v40, v40 quad_perm:[1,0,3,2] row_mask:0xf bank_mask:0xf bound_ctrl:1
	v_add_f32_dpp v42, v42, v42 quad_perm:[1,0,3,2] row_mask:0xf bank_mask:0xf bound_ctrl:1
	v_add_f32_dpp v44, v44, v44 quad_perm:[1,0,3,2] row_mask:0xf bank_mask:0xf bound_ctrl:1
	v_add_f32_dpp v46, v46, v46 quad_perm:[1,0,3,2] row_mask:0xf bank_mask:0xf bound_ctrl:1
	v_pk_fma_f32 v[12:13], v[12:13], v[104:105], v[88:89]
	v_pk_fma_f32 v[4:5], v[4:5], v[104:105], v[90:91]
	v_pk_fma_f32 v[14:15], v[14:15], v[106:107], v[92:93]
	v_pk_fma_f32 v[6:7], v[6:7], v[106:107], v[94:95]
	v_add_f32_dpp v40, v40, v40 quad_perm:[2,3,0,1] row_mask:0xf bank_mask:0xf bound_ctrl:1
	v_add_f32_dpp v42, v42, v42 quad_perm:[2,3,0,1] row_mask:0xf bank_mask:0xf bound_ctrl:1
	v_add_f32_dpp v44, v44, v44 quad_perm:[2,3,0,1] row_mask:0xf bank_mask:0xf bound_ctrl:1
	v_add_f32_dpp v46, v46, v46 quad_perm:[2,3,0,1] row_mask:0xf bank_mask:0xf bound_ctrl:1
	v_pk_mul_f32 v[88:89], v[132:133], v[98:99] op_sel_hi:[1,0]
	v_pk_mul_f32 v[90:91], v[132:133], v[98:99] op_sel:[0,1] op_sel_hi:[1,1]
	v_pk_mul_f32 v[92:93], v[134:135], v[98:99] op_sel_hi:[1,0]
	v_pk_mul_f32 v[94:95], v[134:135], v[98:99] op_sel:[0,1] op_sel_hi:[1,1]
	v_add_f32_dpp v40, v40, v40 row_half_mirror row_mask:0xf bank_mask:0xf bound_ctrl:1
	v_add_f32_dpp v42, v42, v42 row_half_mirror row_mask:0xf bank_mask:0xf bound_ctrl:1
	v_add_f32_dpp v44, v44, v44 row_half_mirror row_mask:0xf bank_mask:0xf bound_ctrl:1
	v_add_f32_dpp v46, v46, v46 row_half_mirror row_mask:0xf bank_mask:0xf bound_ctrl:1
	v_pk_fma_f32 v[8:9], v[8:9], v[108:109], v[88:89]
	v_pk_fma_f32 v[0:1], v[0:1], v[108:109], v[90:91]
	v_pk_fma_f32 v[10:11], v[10:11], v[110:111], v[92:93]
	v_pk_fma_f32 v[2:3], v[2:3], v[110:111], v[94:95]
	v_pk_fma_f32 v[12:13], v[120:121], v[40:41], v[12:13] op_sel_hi:[1,0,1] neg_lo:[0,1,0] neg_hi:[0,1,0]
	v_pk_fma_f32 v[4:5], v[120:121], v[42:43], v[4:5] op_sel_hi:[1,0,1] neg_lo:[0,1,0] neg_hi:[0,1,0]
	v_pk_fma_f32 v[14:15], v[122:123], v[40:41], v[14:15] op_sel_hi:[1,0,1] neg_lo:[0,1,0] neg_hi:[0,1,0]
	v_pk_fma_f32 v[6:7], v[122:123], v[42:43], v[6:7] op_sel_hi:[1,0,1] neg_lo:[0,1,0] neg_hi:[0,1,0]
	v_pk_fma_f32 v[8:9], v[124:125], v[40:41], v[8:9] op_sel_hi:[1,0,1] neg_lo:[0,1,0] neg_hi:[0,1,0]
	v_pk_fma_f32 v[0:1], v[124:125], v[42:43], v[0:1] op_sel_hi:[1,0,1] neg_lo:[0,1,0] neg_hi:[0,1,0]
	v_pk_fma_f32 v[10:11], v[126:127], v[40:41], v[10:11] op_sel_hi:[1,0,1] neg_lo:[0,1,0] neg_hi:[0,1,0]
	v_pk_fma_f32 v[2:3], v[126:127], v[42:43], v[2:3] op_sel_hi:[1,0,1] neg_lo:[0,1,0] neg_hi:[0,1,0]
	s_and_saveexec_b64 s[42:43], s[6:7]
	ds_write2_b32 v168, v44, v46 offset0:0 offset1:8
	s_mov_b64 exec, s[42:43]
	ds_read_b128 v[104:107], v166 offset:768
	ds_read_b128 v[108:111], v166 offset:784
	ds_read_b128 v[112:115], v166 offset:4864
	ds_read_b128 v[116:119], v166 offset:4880
	ds_read_b128 v[120:123], v166 offset:8960
	ds_read_b128 v[124:127], v166 offset:8976
	ds_read_b128 v[128:131], v166 offset:13056
	ds_read_b128 v[132:135], v166 offset:13072
	ds_read_b128 v[136:139], v166 offset:16896
	ds_read_b128 v[140:143], v166 offset:16912
	ds_read2_b32 v[98:99], v167 offset0:192 offset1:200
	s_waitcnt lgkmcnt(12)
; #define LAS __attribute__((address_space(3)))
; template <int CTRL> __device__ __forceinline__ float dpp_f(float x) { return __builtin_bit_cast(float, __builtin_amdgcn_mov_dpp(__builtin_bit_cast(int, x), CTRL, 0xf, 0xf, true)); }
; __device__ __forceinline__ float red8(float d) { d += dpp_f<0xB1>(d); d += dpp_f<0x4E>(d); d += dpp_f<0x141>(d); return d; }
; __device__ __forceinline__ void upd8(V8& S, const V8& w, const V8& b, const V8& k, float sa, float vv) {
;     const f32x2 sa2 = {sa, sa}, vv2 = {vv, vv};
; #pragma unroll
;     for (int i = 0; i < 4; ++i) { f32x2 t = vv2 * k.p[i]; t = sa2 * b.p[i] + t; S.p[i] = S.p[i] * w.p[i] + t; }
; template <int MODE>
; __device__ __forceinline__ void scan_pair(LAS unsigned char* lds, CArgsP a, const ScanUnit u, int nch) {
;     ...
;         for (int t = 0; t < 16; ++t) {
;             const LAS float* p = cb + t * 64 + 8 * ks;
;             const V8 w = ld8(p), kk = ld8(p + 1024), bb = ld8(p + 2048), kv = ld8(p + 3072);
;             const float va = cb[(5 * 16 + t) * 64 + vr0], vb = cb[(5 * 16 + t) * 64 + vr1];
;             float da = dot8(Sa, kk), db = dot8(Sb, kk);
;             da = red8(da); db = red8(db);
;             upd8(Sa, w, bb, kv, -da, va); upd8(Sb, w, bb, kv, -db, vb);
;             if (MODE == 1) {
;                 float pa = dot8(Pa, kk), pb = dot8(Pb, kk);
;                 pa = red8(pa); pb = red8(pb);
;                 updp8(Pa, w, bb, -pa); updp8(Pb, w, bb, -pb);
;             } else {
;                 const V8 rr = ld8(p + 4096);
;                 float ya = dot8(Sa, rr), yb = dot8(Sb, rr);
;                 ya = red8(ya); yb = red8(yb);
;                 if (ks == 0) { Y[t * 64 + vr0] = ya; Y[t * 64 + vr1] = yb; }
;             }
	v_pk_mul_f32 v[40:41], v[12:13], v[216:217]
	v_pk_mul_f32 v[42:43], v[4:5], v[216:217]
	v_pk_mul_f32 v[44:45], v[12:13], v[240:241]
	v_pk_mul_f32 v[46:47], v[4:5], v[240:241]
	v_pk_fma_f32 v[40:41], v[14:15], v[218:219], v[40:41]
	v_pk_fma_f32 v[42:43], v[6:7], v[218:219], v[42:43]
	v_pk_fma_f32 v[44:45], v[14:15], v[242:243], v[44:45]
	v_pk_fma_f32 v[46:47], v[6:7], v[242:243], v[46:47]
	v_pk_fma_f32 v[40:41], v[8:9], v[220:221], v[40:41]
	v_pk_fma_f32 v[42:43], v[0:1], v[220:221], v[42:43]
	v_pk_fma_f32 v[44:45], v[8:9], v[244:245], v[44:45]
	v_pk_fma_f32 v[46:47], v[0:1], v[244:245], v[46:47]
	v_pk_fma_f32 v[40:41], v[10:11], v[222:223], v[40:41]
	v_pk_fma_f32 v[42:43], v[2:3], v[222:223], v[42:43]
	v_pk_fma_f32 v[44:45], v[10:11], v[246:247], v[44:45]
	v_pk_fma_f32 v[46:47], v[2:3], v[246:247], v[46:47]
	v_add_f32_e32 v40, v40, v41
	v_add_f32_e32 v42, v42, v43
	v_add_f32_e32 v44, v44, v45
	v_add_f32_e32 v46, v46, v47
	v_pk_mul_f32 v[88:89], v[232:233], v[248:249] op_sel_hi:[1,0]
	v_pk_mul_f32 v[90:91], v[232:233], v[248:249] op_sel:[0,1] op_sel_hi:[1,1]
	v_pk_mul_f32 v[92:93], v[234:235], v[248:249] op_sel_hi:[1,0]
	v_pk_mul_f32 v[94:95], v[234:235], v[248:249] op_sel:[0,1] op_sel_hi:[1,1]
	v_add_f32_dpp v40, v40, v40 quad_perm:[1,0,3,2] row_mask:0xf bank_mask:0xf bound_ctrl:1
	v_add_f32_dpp v42, v42, v42 quad_perm:[1,0,3,2] row_mask:0xf bank_mask:0xf bound_ctrl:1
	v_add_f32_dpp v44, v44, v44 quad_perm:[1,0,3,2] row_mask:0xf bank_mask:0xf bound_ctrl:1
	v_add_f32_dpp v46, v46, v46 quad_perm:[1,0,3,2] row_mask:0xf bank_mask:0xf bound_ctrl:1
	v_pk_fma_f32 v[12:13], v[12:13], v[208:209], v[88:89]
	v_pk_fma_f32 v[4:5], v[4:5], v[208:209], v[90:91]
	v_pk_fma_f32 v[14:15], v[14:15], v[210:211], v[92:93]
	v_pk_fma_f32 v[6:7], v[6:7], v[210:211], v[94:95]
	v_add_f32_dpp v40, v40, v40 quad_perm:[2,3,0,1] row_mask:0xf bank_mask:0xf bound_ctrl:1
	v_add_f32_dpp v42, v42, v42 quad_perm:[2,3,0,1] row_mask:0xf bank_mask:0xf bound_ctrl:1
	v_add_f32_dpp v44, v44, v44 quad_perm:[2,3,0,1] row_mask:0xf bank_mask:0xf bound_ctrl:1
	v_add_f32_dpp v46, v46, v46 quad_perm:[2,3,0,1] row_mask:0xf bank_mask:0xf bound_ctrl:1
	v_pk_mul_f32 v[88:89], v[236:237], v[248:249] op_sel_hi:[1,0]
	v_pk_mul_f32 v[90:91], v[236:237], v[248:249] op_sel:[0,1] op_sel_hi:[1,1]
	v_pk_mul_f32 v[92:93], v[238:239], v[248:249] op_sel_hi:[1,0]
	v_pk_mul_f32 v[94:95], v[238:239], v[248:249] op_sel:[0,1] op_sel_hi:[1,1]
	v_add_f32_dpp v40, v40, v40 row_half_mirror row_mask:0xf bank_mask:0xf bound_ctrl:1
	v_add_f32_dpp v42, v42, v42 row_half_mirror row_mask:0xf bank_mask:0xf bound_ctrl:1
	v_add_f32_dpp v44, v44, v44 row_half_mirror row_mask:0xf bank_mask:0xf bound_ctrl:1
	v_add_f32_dpp v46, v46, v46 row_half_mirror row_mask:0xf bank_mask:0xf bound_ctrl:1
	v_pk_fma_f32 v[8:9], v[8:9], v[212:213], v[88:89]
	v_pk_fma_f32 v[0:1], v[0:1], v[212:213], v[90:91]
	v_pk_fma_f32 v[10:11], v[10:11], v[214:215], v[92:93]
	v_pk_fma_f32 v[2:3], v[2:3], v[214:215], v[94:95]
	v_pk_fma_f32 v[12:13], v[224:225], v[40:41], v[12:13] op_sel_hi:[1,0,1] neg_lo:[0,1,0] neg_hi:[0,1,0]
	v_pk_fma_f32 v[4:5], v[224:225], v[42:43], v[4:5] op_sel_hi:[1,0,1] neg_lo:[0,1,0] neg_hi:[0,1,0]
	v_pk_fma_f32 v[14:15], v[226:227], v[40:41], v[14:15] op_sel_hi:[1,0,1] neg_lo:[0,1,0] neg_hi:[0,1,0]
	v_pk_fma_f32 v[6:7], v[226:227], v[42:43], v[6:7] op_sel_hi:[1,0,1] neg_lo:[0,1,0] neg_hi:[0,1,0]
	v_pk_fma_f32 v[8:9], v[228:229], v[40:41], v[8:9] op_sel_hi:[1,0,1] neg_lo:[0,1,0] neg_hi:[0,1,0]
	v_pk_fma_f32 v[0:1], v[228:229], v[42:43], v[0:1] op_sel_hi:[1,0,1] neg_lo:[0,1,0] neg_hi:[0,1,0]
	v_pk_fma_f32 v[10:11], v[230:231], v[40:41], v[10:11] op_sel_hi:[1,0,1] neg_lo:[0,1,0] neg_hi:[0,1,0]
	v_pk_fma_f32 v[2:3], v[230:231], v[42:43], v[2:3] op_sel_hi:[1,0,1] neg_lo:[0,1,0] neg_hi:[0,1,0]
	s_and_saveexec_b64 s[42:43], s[6:7]
	ds_write2_b32 v168, v44, v46 offset0:64 offset1:72
	s_mov_b64 exec, s[42:43]
	ds_read_b128 v[208:211], v166 offset:1024
	ds_read_b128 v[212:215], v166 offset:1040
	ds_read_b128 v[216:219], v166 offset:5120
	ds_read_b128 v[220:223], v166 offset:5136
	ds_read_b128 v[224:227], v166 offset:9216
	ds_read_b128 v[228:231], v166 offset:9232
	ds_read_b128 v[232:235], v166 offset:13312
	ds_read_b128 v[236:239], v166 offset:13328
	ds_read_b128 v[240:243], v166 offset:17152
	ds_read_b128 v[244:247], v166 offset:17168
	v_add_u32_e32 v167, 0x400, v167
	ds_read2_b32 v[248:249], v167 offset0:0 offset1:8
	s_waitcnt lgkmcnt(12)
; #define LAS __attribute__((address_space(3)))
; template <int CTRL> __device__ __forceinline__ float dpp_f(float x) { return __builtin_bit_cast(float, __builtin_amdgcn_mov_dpp(__builtin_bit_cast(int, x), CTRL, 0xf, 0xf, true)); }
; __device__ __forceinline__ float red8(float d) { d += dpp_f<0xB1>(d); d += dpp_f<0x4E>(d); d += dpp_f<0x141>(d); return d; }
; __device__ __forceinline__ void upd8(V8& S, const V8& w, const V8& b, const V8& k, float sa, float vv) {
;     const f32x2 sa2 = {sa, sa}, vv2 = {vv, vv};
; #pragma unroll
;     for (int i = 0; i < 4; ++i) { f32x2 t = vv2 * k.p[i]; t = sa2 * b.p[i] + t; S.p[i] = S.p[i] * w.p[i] + t; }
; template <int MODE>
; __device__ __forceinline__ void scan_pair(LAS unsigned char* lds, CArgsP a, const ScanUnit u, int nch) {
;     ...
;         for (int t = 0; t < 16; ++t) {
;             const LAS float* p = cb + t * 64 + 8 * ks;
;             const V8 w = ld8(p), kk = ld8(p + 1024), bb = ld8(p + 2048), kv = ld8(p + 3072);
;             const float va = cb[(5 * 16 + t) * 64 + vr0], vb = cb[(5 * 16 + t) * 64 + vr1];
;             float da = dot8(Sa, kk), db = dot8(Sb, kk);
;             da = red8(da); db = red8(db);
;             upd8(Sa, w, bb, kv, -da, va); upd8(Sb, w, bb, kv, -db, vb);
;             if (MODE == 1) {
;                 float pa = dot8(Pa, kk), pb = dot8(Pb, kk);
;                 pa = red8(pa); pb = red8(pb);
;                 updp8(Pa, w, bb, -pa); updp8(Pb, w, bb, -pb);
;             } else {
;                 const V8 rr = ld8(p + 4096);
;                 float ya = dot8(Sa, rr), yb = dot8(Sb, rr);
;                 ya = red8(ya); yb = red8(yb);
;                 if (ks == 0) { Y[t * 64 + vr0] = ya; Y[t * 64 + vr1] = yb; }
;             }
	v_pk_mul_f32 v[40:41], v[12:13], v[112:113]
	v_pk_mul_f32 v[42:43], v[4:5], v[112:113]
	v_pk_mul_f32 v[44:45], v[12:13], v[136:137]
	v_pk_mul_f32 v[46:47], v[4:5], v[136:137]
	v_pk_fma_f32 v[40:41], v[14:15], v[114:115], v[40:41]
	v_pk_fma_f32 v[42:43], v[6:7], v[114:115], v[42:43]
	v_pk_fma_f32 v[44:45], v[14:15], v[138:139], v[44:45]
	v_pk_fma_f32 v[46:47], v[6:7], v[138:139], v[46:47]
	v_pk_fma_f32 v[40:41], v[8:9], v[116:117], v[40:41]
	v_pk_fma_f32 v[42:43], v[0:1], v[116:117], v[42:43]
	v_pk_fma_f32 v[44:45], v[8:9], v[140:141], v[44:45]
	v_pk_fma_f32 v[46:47], v[0:1], v[140:141], v[46:47]
	v_pk_fma_f32 v[40:41], v[10:11], v[118:119], v[40:41]
	v_pk_fma_f32 v[42:43], v[2:3], v[118:119], v[42:43]
	v_pk_fma_f32 v[44:45], v[10:11], v[142:143], v[44:45]
	v_pk_fma_f32 v[46:47], v[2:3], v[142:143], v[46:47]
	v_add_f32_e32 v40, v40, v41
	v_add_f32_e32 v42, v42, v43
	v_add_f32_e32 v44, v44, v45
	v_add_f32_e32 v46, v46, v47
	v_pk_mul_f32 v[88:89], v[128:129], v[98:99] op_sel_hi:[1,0]
	v_pk_mul_f32 v[90:91], v[128:129], v[98:99] op_sel:[0,1] op_sel_hi:[1,1]
	v_pk_mul_f32 v[92:93], v[130:131], v[98:99] op_sel_hi:[1,0]
	v_pk_mul_f32 v[94:95], v[130:131], v[98:99] op_sel:[0,1] op_sel_hi:[1,1]
	v_add_f32_dpp v40, v40, v40 quad_perm:[1,0,3,2] row_mask:0xf bank_mask:0xf bound_ctrl:1
	v_add_f32_dpp v42, v42, v42 quad_perm:[1,0,3,2] row_mask:0xf bank_mask:0xf bound_ctrl:1
	v_add_f32_dpp v44, v44, v44 quad_perm:[1,0,3,2] row_mask:0xf bank_mask:0xf bound_ctrl:1
	v_add_f32_dpp v46, v46, v46 quad_perm:[1,0,3,2] row_mask:0xf bank_mask:0xf bound_ctrl:1
	v_pk_fma_f32 v[12:13], v[12:13], v[104:105], v[88:89]
	v_pk_fma_f32 v[4:5], v[4:5], v[104:105], v[90:91]
	v_pk_fma_f32 v[14:15], v[14:15], v[106:107], v[92:93]
	v_pk_fma_f32 v[6:7], v[6:7], v[106:107], v[94:95]
	v_add_f32_dpp v40, v40, v40 quad_perm:[2,3,0,1] row_mask:0xf bank_mask:0xf bound_ctrl:1
	v_add_f32_dpp v42, v42, v42 quad_perm:[2,3,0,1] row_mask:0xf bank_mask:0xf bound_ctrl:1
	v_add_f32_dpp v44, v44, v44 quad_perm:[2,3,0,1] row_mask:0xf bank_mask:0xf bound_ctrl:1
	v_add_f32_dpp v46, v46, v46 quad_perm:[2,3,0,1] row_mask:0xf bank_mask:0xf bound_ctrl:1
	v_pk_mul_f32 v[88:89], v[132:133], v[98:99] op_sel_hi:[1,0]
	v_pk_mul_f32 v[90:91], v[132:133], v[98:99] op_sel:[0,1] op_sel_hi:[1,1]
	v_pk_mul_f32 v[92:93], v[134:135], v[98:99] op_sel_hi:[1,0]
	v_pk_mul_f32 v[94:95], v[134:135], v[98:99] op_sel:[0,1] op_sel_hi:[1,1]
	v_add_f32_dpp v40, v40, v40 row_half_mirror row_mask:0xf bank_mask:0xf bound_ctrl:1
	v_add_f32_dpp v42, v42, v42 row_half_mirror row_mask:0xf bank_mask:0xf bound_ctrl:1
	v_add_f32_dpp v44, v44, v44 row_half_mirror row_mask:0xf bank_mask:0xf bound_ctrl:1
	v_add_f32_dpp v46, v46, v46 row_half_mirror row_mask:0xf bank_mask:0xf bound_ctrl:1
	v_pk_fma_f32 v[8:9], v[8:9], v[108:109], v[88:89]
	v_pk_fma_f32 v[0:1], v[0:1], v[108:109], v[90:91]
	v_pk_fma_f32 v[10:11], v[10:11], v[110:111], v[92:93]
	v_pk_fma_f32 v[2:3], v[2:3], v[110:111], v[94:95]
	v_pk_fma_f32 v[12:13], v[120:121], v[40:41], v[12:13] op_sel_hi:[1,0,1] neg_lo:[0,1,0] neg_hi:[0,1,0]
	v_pk_fma_f32 v[4:5], v[120:121], v[42:43], v[4:5] op_sel_hi:[1,0,1] neg_lo:[0,1,0] neg_hi:[0,1,0]
	v_pk_fma_f32 v[14:15], v[122:123], v[40:41], v[14:15] op_sel_hi:[1,0,1] neg_lo:[0,1,0] neg_hi:[0,1,0]
	v_pk_fma_f32 v[6:7], v[122:123], v[42:43], v[6:7] op_sel_hi:[1,0,1] neg_lo:[0,1,0] neg_hi:[0,1,0]
	v_pk_fma_f32 v[8:9], v[124:125], v[40:41], v[8:9] op_sel_hi:[1,0,1] neg_lo:[0,1,0] neg_hi:[0,1,0]
	v_pk_fma_f32 v[0:1], v[124:125], v[42:43], v[0:1] op_sel_hi:[1,0,1] neg_lo:[0,1,0] neg_hi:[0,1,0]
	v_pk_fma_f32 v[10:11], v[126:127], v[40:41], v[10:11] op_sel_hi:[1,0,1] neg_lo:[0,1,0] neg_hi:[0,1,0]
	v_pk_fma_f32 v[2:3], v[126:127], v[42:43], v[2:3] op_sel_hi:[1,0,1] neg_lo:[0,1,0] neg_hi:[0,1,0]
	s_and_saveexec_b64 s[42:43], s[6:7]
	ds_write2_b32 v168, v44, v46 offset0:128 offset1:136
	s_mov_b64 exec, s[42:43]
	ds_read_b128 v[104:107], v166 offset:1280
	ds_read_b128 v[108:111], v166 offset:1296
	ds_read_b128 v[112:115], v166 offset:5376
	ds_read_b128 v[116:119], v166 offset:5392
	ds_read_b128 v[120:123], v166 offset:9472
	ds_read_b128 v[124:127], v166 offset:9488
	ds_read_b128 v[128:131], v166 offset:13568
	ds_read_b128 v[132:135], v166 offset:13584
	ds_read_b128 v[136:139], v166 offset:17408
	ds_read_b128 v[140:143], v166 offset:17424
	ds_read2_b32 v[98:99], v167 offset0:64 offset1:72
	s_waitcnt lgkmcnt(12)
; #define LAS __attribute__((address_space(3)))
; template <int CTRL> __device__ __forceinline__ float dpp_f(float x) { return __builtin_bit_cast(float, __builtin_amdgcn_mov_dpp(__builtin_bit_cast(int, x), CTRL, 0xf, 0xf, true)); }
; __device__ __forceinline__ float red8(float d) { d += dpp_f<0xB1>(d); d += dpp_f<0x4E>(d); d += dpp_f<0x141>(d); return d; }
; __device__ __forceinline__ void upd8(V8& S, const V8& w, const V8& b, const V8& k, float sa, float vv) {
;     const f32x2 sa2 = {sa, sa}, vv2 = {vv, vv};
; #pragma unroll
;     for (int i = 0; i < 4; ++i) { f32x2 t = vv2 * k.p[i]; t = sa2 * b.p[i] + t; S.p[i] = S.p[i] * w.p[i] + t; }
; template <int MODE>
; __device__ __forceinline__ void scan_pair(LAS unsigned char* lds, CArgsP a, const ScanUnit u, int nch) {
;     ...
;         for (int t = 0; t < 16; ++t) {
;             const LAS float* p = cb + t * 64 + 8 * ks;
;             const V8 w = ld8(p), kk = ld8(p + 1024), bb = ld8(p + 2048), kv = ld8(p + 3072);
;             const float va = cb[(5 * 16 + t) * 64 + vr0], vb = cb[(5 * 16 + t) * 64 + vr1];
;             float da = dot8(Sa, kk), db = dot8(Sb, kk);
;             da = red8(da); db = red8(db);
;             upd8(Sa, w, bb, kv, -da, va); upd8(Sb, w, bb, kv, -db, vb);
;             if (MODE == 1) {
;                 float pa = dot8(Pa, kk), pb = dot8(Pb, kk);
;                 pa = red8(pa); pb = red8(pb);
;                 updp8(Pa, w, bb, -pa); updp8(Pb, w, bb, -pb);
;             } else {
;                 const V8 rr = ld8(p + 4096);
;                 float ya = dot8(Sa, rr), yb = dot8(Sb, rr);
;                 ya = red8(ya); yb = red8(yb);
;                 if (ks == 0) { Y[t * 64 + vr0] = ya; Y[t * 64 + vr1] = yb; }
;             }
	v_pk_mul_f32 v[40:41], v[12:13], v[216:217]
	v_pk_mul_f32 v[42:43], v[4:5], v[216:217]
	v_pk_mul_f32 v[44:45], v[12:13], v[240:241]
	v_pk_mul_f32 v[46:47], v[4:5], v[240:241]
	v_pk_fma_f32 v[40:41], v[14:15], v[218:219], v[40:41]
	v_pk_fma_f32 v[42:43], v[6:7], v[218:219], v[42:43]
	v_pk_fma_f32 v[44:45], v[14:15], v[242:243], v[44:45]
	v_pk_fma_f32 v[46:47], v[6:7], v[242:243], v[46:47]
	v_pk_fma_f32 v[40:41], v[8:9], v[220:221], v[40:41]
	v_pk_fma_f32 v[42:43], v[0:1], v[220:221], v[42:43]
	v_pk_fma_f32 v[44:45], v[8:9], v[244:245], v[44:45]
	v_pk_fma_f32 v[46:47], v[0:1], v[244:245], v[46:47]
	v_pk_fma_f32 v[40:41], v[10:11], v[222:223], v[40:41]
	v_pk_fma_f32 v[42:43], v[2:3], v[222:223], v[42:43]
	v_pk_fma_f32 v[44:45], v[10:11], v[246:247], v[44:45]
	v_pk_fma_f32 v[46:47], v[2:3], v[246:247], v[46:47]
	v_add_f32_e32 v40, v40, v41
	v_add_f32_e32 v42, v42, v43
	v_add_f32_e32 v44, v44, v45
	v_add_f32_e32 v46, v46, v47
	v_pk_mul_f32 v[88:89], v[232:233], v[248:249] op_sel_hi:[1,0]
	v_pk_mul_f32 v[90:91], v[232:233], v[248:249] op_sel:[0,1] op_sel_hi:[1,1]
	v_pk_mul_f32 v[92:93], v[234:235], v[248:249] op_sel_hi:[1,0]
	v_pk_mul_f32 v[94:95], v[234:235], v[248:249] op_sel:[0,1] op_sel_hi:[1,1]
	v_add_f32_dpp v40, v40, v40 quad_perm:[1,0,3,2] row_mask:0xf bank_mask:0xf bound_ctrl:1
	v_add_f32_dpp v42, v42, v42 quad_perm:[1,0,3,2] row_mask:0xf bank_mask:0xf bound_ctrl:1
	v_add_f32_dpp v44, v44, v44 quad_perm:[1,0,3,2] row_mask:0xf bank_mask:0xf bound_ctrl:1
	v_add_f32_dpp v46, v46, v46 quad_perm:[1,0,3,2] row_mask:0xf bank_mask:0xf bound_ctrl:1
	v_pk_fma_f32 v[12:13], v[12:13], v[208:209], v[88:89]
	v_pk_fma_f32 v[4:5], v[4:5], v[208:209], v[90:91]
	v_pk_fma_f32 v[14:15], v[14:15], v[210:211], v[92:93]
	v_pk_fma_f32 v[6:7], v[6:7], v[210:211], v[94:95]
	v_add_f32_dpp v40, v40, v40 quad_perm:[2,3,0,1] row_mask:0xf bank_mask:0xf bound_ctrl:1
	v_add_f32_dpp v42, v42, v42 quad_perm:[2,3,0,1] row_mask:0xf bank_mask:0xf bound_ctrl:1
	v_add_f32_dpp v44, v44, v44 quad_perm:[2,3,0,1] row_mask:0xf bank_mask:0xf bound_ctrl:1
	v_add_f32_dpp v46, v46, v46 quad_perm:[2,3,0,1] row_mask:0xf bank_mask:0xf bound_ctrl:1
	v_pk_mul_f32 v[88:89], v[236:237], v[248:249] op_sel_hi:[1,0]
	v_pk_mul_f32 v[90:91], v[236:237], v[248:249] op_sel:[0,1] op_sel_hi:[1,1]
	v_pk_mul_f32 v[92:93], v[238:239], v[248:249] op_sel_hi:[1,0]
	v_pk_mul_f32 v[94:95], v[238:239], v[248:249] op_sel:[0,1] op_sel_hi:[1,1]
	v_add_f32_dpp v40, v40, v40 row_half_mirror row_mask:0xf bank_mask:0xf bound_ctrl:1
	v_add_f32_dpp v42, v42, v42 row_half_mirror row_mask:0xf bank_mask:0xf bound_ctrl:1
	v_add_f32_dpp v44, v44, v44 row_half_mirror row_mask:0xf bank_mask:0xf bound_ctrl:1
	v_add_f32_dpp v46, v46, v46 row_half_mirror row_mask:0xf bank_mask:0xf bound_ctrl:1
	v_pk_fma_f32 v[8:9], v[8:9], v[212:213], v[88:89]
	v_pk_fma_f32 v[0:1], v[0:1], v[212:213], v[90:91]
	v_pk_fma_f32 v[10:11], v[10:11], v[214:215], v[92:93]
	v_pk_fma_f32 v[2:3], v[2:3], v[214:215], v[94:95]
	v_pk_fma_f32 v[12:13], v[224:225], v[40:41], v[12:13] op_sel_hi:[1,0,1] neg_lo:[0,1,0] neg_hi:[0,1,0]
	v_pk_fma_f32 v[4:5], v[224:225], v[42:43], v[4:5] op_sel_hi:[1,0,1] neg_lo:[0,1,0] neg_hi:[0,1,0]
	v_pk_fma_f32 v[14:15], v[226:227], v[40:41], v[14:15] op_sel_hi:[1,0,1] neg_lo:[0,1,0] neg_hi:[0,1,0]
	v_pk_fma_f32 v[6:7], v[226:227], v[42:43], v[6:7] op_sel_hi:[1,0,1] neg_lo:[0,1,0] neg_hi:[0,1,0]
	v_pk_fma_f32 v[8:9], v[228:229], v[40:41], v[8:9] op_sel_hi:[1,0,1] neg_lo:[0,1,0] neg_hi:[0,1,0]
	v_pk_fma_f32 v[0:1], v[228:229], v[42:43], v[0:1] op_sel_hi:[1,0,1] neg_lo:[0,1,0] neg_hi:[0,1,0]
	v_pk_fma_f32 v[10:11], v[230:231], v[40:41], v[10:11] op_sel_hi:[1,0,1] neg_lo:[0,1,0] neg_hi:[0,1,0]
	v_pk_fma_f32 v[2:3], v[230:231], v[42:43], v[2:3] op_sel_hi:[1,0,1] neg_lo:[0,1,0] neg_hi:[0,1,0]
	s_and_saveexec_b64 s[42:43], s[6:7]
	ds_write2_b32 v168, v44, v46 offset0:192 offset1:200
	s_mov_b64 exec, s[42:43]
	ds_read_b128 v[208:211], v166 offset:1536
	ds_read_b128 v[212:215], v166 offset:1552
	ds_read_b128 v[216:219], v166 offset:5632
	ds_read_b128 v[220:223], v166 offset:5648
	ds_read_b128 v[224:227], v166 offset:9728
	ds_read_b128 v[228:231], v166 offset:9744
	ds_read_b128 v[232:235], v166 offset:13824
	ds_read_b128 v[236:239], v166 offset:13840
	ds_read_b128 v[240:243], v166 offset:17664
	ds_read_b128 v[244:247], v166 offset:17680
	ds_read2_b32 v[248:249], v167 offset0:128 offset1:136
	s_waitcnt lgkmcnt(12)
; #define LAS __attribute__((address_space(3)))
; template <int CTRL> __device__ __forceinline__ float dpp_f(float x) { return __builtin_bit_cast(float, __builtin_amdgcn_mov_dpp(__builtin_bit_cast(int, x), CTRL, 0xf, 0xf, true)); }
; __device__ __forceinline__ float red8(float d) { d += dpp_f<0xB1>(d); d += dpp_f<0x4E>(d); d += dpp_f<0x141>(d); return d; }
; __device__ __forceinline__ void upd8(V8& S, const V8& w, const V8& b, const V8& k, float sa, float vv) {
;     const f32x2 sa2 = {sa, sa}, vv2 = {vv, vv};
; #pragma unroll
;     for (int i = 0; i < 4; ++i) { f32x2 t = vv2 * k.p[i]; t = sa2 * b.p[i] + t; S.p[i] = S.p[i] * w.p[i] + t; }
; template <int MODE>
; __device__ __forceinline__ void scan_pair(LAS unsigned char* lds, CArgsP a, const ScanUnit u, int nch) {
;     ...
;         for (int t = 0; t < 16; ++t) {
;             const LAS float* p = cb + t * 64 + 8 * ks;
;             const V8 w = ld8(p), kk = ld8(p + 1024), bb = ld8(p + 2048), kv = ld8(p + 3072);
;             const float va = cb[(5 * 16 + t) * 64 + vr0], vb = cb[(5 * 16 + t) * 64 + vr1];
;             float da = dot8(Sa, kk), db = dot8(Sb, kk);
;             da = red8(da); db = red8(db);
;             upd8(Sa, w, bb, kv, -da, va); upd8(Sb, w, bb, kv, -db, vb);
;             if (MODE == 1) {
;                 float pa = dot8(Pa, kk), pb = dot8(Pb, kk);
;                 pa = red8(pa); pb = red8(pb);
;                 updp8(Pa, w, bb, -pa); updp8(Pb, w, bb, -pb);
;             } else {
;                 const V8 rr = ld8(p + 4096);
;                 float ya = dot8(Sa, rr), yb = dot8(Sb, rr);
;                 ya = red8(ya); yb = red8(yb);
;                 if (ks == 0) { Y[t * 64 + vr0] = ya; Y[t * 64 + vr1] = yb; }
;             }
	v_pk_mul_f32 v[40:41], v[12:13], v[112:113]
	v_pk_mul_f32 v[42:43], v[4:5], v[112:113]
	v_pk_mul_f32 v[44:45], v[12:13], v[136:137]
	v_pk_mul_f32 v[46:47], v[4:5], v[136:137]
	v_pk_fma_f32 v[40:41], v[14:15], v[114:115], v[40:41]
	v_pk_fma_f32 v[42:43], v[6:7], v[114:115], v[42:43]
	v_pk_fma_f32 v[44:45], v[14:15], v[138:139], v[44:45]
	v_pk_fma_f32 v[46:47], v[6:7], v[138:139], v[46:47]
	v_pk_fma_f32 v[40:41], v[8:9], v[116:117], v[40:41]
	v_pk_fma_f32 v[42:43], v[0:1], v[116:117], v[42:43]
	v_pk_fma_f32 v[44:45], v[8:9], v[140:141], v[44:45]
	v_pk_fma_f32 v[46:47], v[0:1], v[140:141], v[46:47]
	v_pk_fma_f32 v[40:41], v[10:11], v[118:119], v[40:41]
	v_pk_fma_f32 v[42:43], v[2:3], v[118:119], v[42:43]
	v_pk_fma_f32 v[44:45], v[10:11], v[142:143], v[44:45]
	v_pk_fma_f32 v[46:47], v[2:3], v[142:143], v[46:47]
	v_add_f32_e32 v40, v40, v41
	v_add_f32_e32 v42, v42, v43
	v_add_f32_e32 v44, v44, v45
	v_add_f32_e32 v46, v46, v47
	v_pk_mul_f32 v[88:89], v[128:129], v[98:99] op_sel_hi:[1,0]
	v_pk_mul_f32 v[90:91], v[128:129], v[98:99] op_sel:[0,1] op_sel_hi:[1,1]
	v_pk_mul_f32 v[92:93], v[130:131], v[98:99] op_sel_hi:[1,0]
	v_pk_mul_f32 v[94:95], v[130:131], v[98:99] op_sel:[0,1] op_sel_hi:[1,1]
	v_add_f32_dpp v40, v40, v40 quad_perm:[1,0,3,2] row_mask:0xf bank_mask:0xf bound_ctrl:1
	v_add_f32_dpp v42, v42, v42 quad_perm:[1,0,3,2] row_mask:0xf bank_mask:0xf bound_ctrl:1
	v_add_f32_dpp v44, v44, v44 quad_perm:[1,0,3,2] row_mask:0xf bank_mask:0xf bound_ctrl:1
	v_add_f32_dpp v46, v46, v46 quad_perm:[1,0,3,2] row_mask:0xf bank_mask:0xf bound_ctrl:1
	v_pk_fma_f32 v[12:13], v[12:13], v[104:105], v[88:89]
	v_pk_fma_f32 v[4:5], v[4:5], v[104:105], v[90:91]
	v_pk_fma_f32 v[14:15], v[14:15], v[106:107], v[92:93]
	v_pk_fma_f32 v[6:7], v[6:7], v[106:107], v[94:95]
	v_add_f32_dpp v40, v40, v40 quad_perm:[2,3,0,1] row_mask:0xf bank_mask:0xf bound_ctrl:1
	v_add_f32_dpp v42, v42, v42 quad_perm:[2,3,0,1] row_mask:0xf bank_mask:0xf bound_ctrl:1
	v_add_f32_dpp v44, v44, v44 quad_perm:[2,3,0,1] row_mask:0xf bank_mask:0xf bound_ctrl:1
	v_add_f32_dpp v46, v46, v46 quad_perm:[2,3,0,1] row_mask:0xf bank_mask:0xf bound_ctrl:1
	v_pk_mul_f32 v[88:89], v[132:133], v[98:99] op_sel_hi:[1,0]
	v_pk_mul_f32 v[90:91], v[132:133], v[98:99] op_sel:[0,1] op_sel_hi:[1,1]
	v_pk_mul_f32 v[92:93], v[134:135], v[98:99] op_sel_hi:[1,0]
	v_pk_mul_f32 v[94:95], v[134:135], v[98:99] op_sel:[0,1] op_sel_hi:[1,1]
	v_add_f32_dpp v40, v40, v40 row_half_mirror row_mask:0xf bank_mask:0xf bound_ctrl:1
	v_add_f32_dpp v42, v42, v42 row_half_mirror row_mask:0xf bank_mask:0xf bound_ctrl:1
	v_add_f32_dpp v44, v44, v44 row_half_mirror row_mask:0xf bank_mask:0xf bound_ctrl:1
	v_add_f32_dpp v46, v46, v46 row_half_mirror row_mask:0xf bank_mask:0xf bound_ctrl:1
	v_pk_fma_f32 v[8:9], v[8:9], v[108:109], v[88:89]
	v_pk_fma_f32 v[0:1], v[0:1], v[108:109], v[90:91]
	v_pk_fma_f32 v[10:11], v[10:11], v[110:111], v[92:93]
	v_pk_fma_f32 v[2:3], v[2:3], v[110:111], v[94:95]
	v_pk_fma_f32 v[12:13], v[120:121], v[40:41], v[12:13] op_sel_hi:[1,0,1] neg_lo:[0,1,0] neg_hi:[0,1,0]
	v_pk_fma_f32 v[4:5], v[120:121], v[42:43], v[4:5] op_sel_hi:[1,0,1] neg_lo:[0,1,0] neg_hi:[0,1,0]
	v_pk_fma_f32 v[14:15], v[122:123], v[40:41], v[14:15] op_sel_hi:[1,0,1] neg_lo:[0,1,0] neg_hi:[0,1,0]
	v_pk_fma_f32 v[6:7], v[122:123], v[42:43], v[6:7] op_sel_hi:[1,0,1] neg_lo:[0,1,0] neg_hi:[0,1,0]
	v_pk_fma_f32 v[8:9], v[124:125], v[40:41], v[8:9] op_sel_hi:[1,0,1] neg_lo:[0,1,0] neg_hi:[0,1,0]
	v_pk_fma_f32 v[0:1], v[124:125], v[42:43], v[0:1] op_sel_hi:[1,0,1] neg_lo:[0,1,0] neg_hi:[0,1,0]
	v_pk_fma_f32 v[10:11], v[126:127], v[40:41], v[10:11] op_sel_hi:[1,0,1] neg_lo:[0,1,0] neg_hi:[0,1,0]
	v_pk_fma_f32 v[2:3], v[126:127], v[42:43], v[2:3] op_sel_hi:[1,0,1] neg_lo:[0,1,0] neg_hi:[0,1,0]
	v_add_u32_e32 v168, 0x400, v168
	s_and_saveexec_b64 s[42:43], s[6:7]
	ds_write2_b32 v168, v44, v46 offset0:0 offset1:8
	s_mov_b64 exec, s[42:43]
	ds_read_b128 v[104:107], v166 offset:1792
	ds_read_b128 v[108:111], v166 offset:1808
	ds_read_b128 v[112:115], v166 offset:5888
	ds_read_b128 v[116:119], v166 offset:5904
	ds_read_b128 v[120:123], v166 offset:9984
	ds_read_b128 v[124:127], v166 offset:10000
	ds_read_b128 v[128:131], v166 offset:14080
	ds_read_b128 v[132:135], v166 offset:14096
	ds_read_b128 v[136:139], v166 offset:17920
	ds_read_b128 v[140:143], v166 offset:17936
	ds_read2_b32 v[98:99], v167 offset0:192 offset1:200
	s_waitcnt lgkmcnt(12)
; #define LAS __attribute__((address_space(3)))
; template <int CTRL> __device__ __forceinline__ float dpp_f(float x) { return __builtin_bit_cast(float, __builtin_amdgcn_mov_dpp(__builtin_bit_cast(int, x), CTRL, 0xf, 0xf, true)); }
; __device__ __forceinline__ float red8(float d) { d += dpp_f<0xB1>(d); d += dpp_f<0x4E>(d); d += dpp_f<0x141>(d); return d; }
; __device__ __forceinline__ void upd8(V8& S, const V8& w, const V8& b, const V8& k, float sa, float vv) {
;     const f32x2 sa2 = {sa, sa}, vv2 = {vv, vv};
; #pragma unroll
;     for (int i = 0; i < 4; ++i) { f32x2 t = vv2 * k.p[i]; t = sa2 * b.p[i] + t; S.p[i] = S.p[i] * w.p[i] + t; }
; template <int MODE>
; __device__ __forceinline__ void scan_pair(LAS unsigned char* lds, CArgsP a, const ScanUnit u, int nch) {
;     ...
;         for (int t = 0; t < 16; ++t) {
;             const LAS float* p = cb + t * 64 + 8 * ks;
;             const V8 w = ld8(p), kk = ld8(p + 1024), bb = ld8(p + 2048), kv = ld8(p + 3072);
;             const float va = cb[(5 * 16 + t) * 64 + vr0], vb = cb[(5 * 16 + t) * 64 + vr1];
;             float da = dot8(Sa, kk), db = dot8(Sb, kk);
;             da = red8(da); db = red8(db);
;             upd8(Sa, w, bb, kv, -da, va); upd8(Sb, w, bb, kv, -db, vb);
;             if (MODE == 1) {
;                 float pa = dot8(Pa, kk), pb = dot8(Pb, kk);
;                 pa = red8(pa); pb = red8(pb);
;                 updp8(Pa, w, bb, -pa); updp8(Pb, w, bb, -pb);
;             } else {
;                 const V8 rr = ld8(p + 4096);
;                 float ya = dot8(Sa, rr), yb = dot8(Sb, rr);
;                 ya = red8(ya); yb = red8(yb);
;                 if (ks == 0) { Y[t * 64 + vr0] = ya; Y[t * 64 + vr1] = yb; }
;             }
	v_pk_mul_f32 v[40:41], v[12:13], v[216:217]
	v_pk_mul_f32 v[42:43], v[4:5], v[216:217]
	v_pk_mul_f32 v[44:45], v[12:13], v[240:241]
	v_pk_mul_f32 v[46:47], v[4:5], v[240:241]
	v_pk_fma_f32 v[40:41], v[14:15], v[218:219], v[40:41]
	v_pk_fma_f32 v[42:43], v[6:7], v[218:219], v[42:43]
	v_pk_fma_f32 v[44:45], v[14:15], v[242:243], v[44:45]
	v_pk_fma_f32 v[46:47], v[6:7], v[242:243], v[46:47]
	v_pk_fma_f32 v[40:41], v[8:9], v[220:221], v[40:41]
	v_pk_fma_f32 v[42:43], v[0:1], v[220:221], v[42:43]
	v_pk_fma_f32 v[44:45], v[8:9], v[244:245], v[44:45]
	v_pk_fma_f32 v[46:47], v[0:1], v[244:245], v[46:47]
	v_pk_fma_f32 v[40:41], v[10:11], v[222:223], v[40:41]
	v_pk_fma_f32 v[42:43], v[2:3], v[222:223], v[42:43]
	v_pk_fma_f32 v[44:45], v[10:11], v[246:247], v[44:45]
	v_pk_fma_f32 v[46:47], v[2:3], v[246:247], v[46:47]
	v_add_f32_e32 v40, v40, v41
	v_add_f32_e32 v42, v42, v43
	v_add_f32_e32 v44, v44, v45
	v_add_f32_e32 v46, v46, v47
	v_pk_mul_f32 v[88:89], v[232:233], v[248:249] op_sel_hi:[1,0]
	v_pk_mul_f32 v[90:91], v[232:233], v[248:249] op_sel:[0,1] op_sel_hi:[1,1]
	v_pk_mul_f32 v[92:93], v[234:235], v[248:249] op_sel_hi:[1,0]
	v_pk_mul_f32 v[94:95], v[234:235], v[248:249] op_sel:[0,1] op_sel_hi:[1,1]
	v_add_f32_dpp v40, v40, v40 quad_perm:[1,0,3,2] row_mask:0xf bank_mask:0xf bound_ctrl:1
	v_add_f32_dpp v42, v42, v42 quad_perm:[1,0,3,2] row_mask:0xf bank_mask:0xf bound_ctrl:1
	v_add_f32_dpp v44, v44, v44 quad_perm:[1,0,3,2] row_mask:0xf bank_mask:0xf bound_ctrl:1
	v_add_f32_dpp v46, v46, v46 quad_perm:[1,0,3,2] row_mask:0xf bank_mask:0xf bound_ctrl:1
	v_pk_fma_f32 v[12:13], v[12:13], v[208:209], v[88:89]
	v_pk_fma_f32 v[4:5], v[4:5], v[208:209], v[90:91]
	v_pk_fma_f32 v[14:15], v[14:15], v[210:211], v[92:93]
	v_pk_fma_f32 v[6:7], v[6:7], v[210:211], v[94:95]
	v_add_f32_dpp v40, v40, v40 quad_perm:[2,3,0,1] row_mask:0xf bank_mask:0xf bound_ctrl:1
	v_add_f32_dpp v42, v42, v42 quad_perm:[2,3,0,1] row_mask:0xf bank_mask:0xf bound_ctrl:1
	v_add_f32_dpp v44, v44, v44 quad_perm:[2,3,0,1] row_mask:0xf bank_mask:0xf bound_ctrl:1
	v_add_f32_dpp v46, v46, v46 quad_perm:[2,3,0,1] row_mask:0xf bank_mask:0xf bound_ctrl:1
	v_pk_mul_f32 v[88:89], v[236:237], v[248:249] op_sel_hi:[1,0]
	v_pk_mul_f32 v[90:91], v[236:237], v[248:249] op_sel:[0,1] op_sel_hi:[1,1]
	v_pk_mul_f32 v[92:93], v[238:239], v[248:249] op_sel_hi:[1,0]
	v_pk_mul_f32 v[94:95], v[238:239], v[248:249] op_sel:[0,1] op_sel_hi:[1,1]
	v_add_f32_dpp v40, v40, v40 row_half_mirror row_mask:0xf bank_mask:0xf bound_ctrl:1
	v_add_f32_dpp v42, v42, v42 row_half_mirror row_mask:0xf bank_mask:0xf bound_ctrl:1
	v_add_f32_dpp v44, v44, v44 row_half_mirror row_mask:0xf bank_mask:0xf bound_ctrl:1
	v_add_f32_dpp v46, v46, v46 row_half_mirror row_mask:0xf bank_mask:0xf bound_ctrl:1
	v_pk_fma_f32 v[8:9], v[8:9], v[212:213], v[88:89]
	v_pk_fma_f32 v[0:1], v[0:1], v[212:213], v[90:91]
	v_pk_fma_f32 v[10:11], v[10:11], v[214:215], v[92:93]
	v_pk_fma_f32 v[2:3], v[2:3], v[214:215], v[94:95]
	v_pk_fma_f32 v[12:13], v[224:225], v[40:41], v[12:13] op_sel_hi:[1,0,1] neg_lo:[0,1,0] neg_hi:[0,1,0]
	v_pk_fma_f32 v[4:5], v[224:225], v[42:43], v[4:5] op_sel_hi:[1,0,1] neg_lo:[0,1,0] neg_hi:[0,1,0]
	v_pk_fma_f32 v[14:15], v[226:227], v[40:41], v[14:15] op_sel_hi:[1,0,1] neg_lo:[0,1,0] neg_hi:[0,1,0]
	v_pk_fma_f32 v[6:7], v[226:227], v[42:43], v[6:7] op_sel_hi:[1,0,1] neg_lo:[0,1,0] neg_hi:[0,1,0]
	v_pk_fma_f32 v[8:9], v[228:229], v[40:41], v[8:9] op_sel_hi:[1,0,1] neg_lo:[0,1,0] neg_hi:[0,1,0]
	v_pk_fma_f32 v[0:1], v[228:229], v[42:43], v[0:1] op_sel_hi:[1,0,1] neg_lo:[0,1,0] neg_hi:[0,1,0]
	v_pk_fma_f32 v[10:11], v[230:231], v[40:41], v[10:11] op_sel_hi:[1,0,1] neg_lo:[0,1,0] neg_hi:[0,1,0]
	v_pk_fma_f32 v[2:3], v[230:231], v[42:43], v[2:3] op_sel_hi:[1,0,1] neg_lo:[0,1,0] neg_hi:[0,1,0]
	s_and_saveexec_b64 s[42:43], s[6:7]
	ds_write2_b32 v168, v44, v46 offset0:64 offset1:72
	s_mov_b64 exec, s[42:43]
	ds_read_b128 v[208:211], v166 offset:2048
	ds_read_b128 v[212:215], v166 offset:2064
	ds_read_b128 v[216:219], v166 offset:6144
	ds_read_b128 v[220:223], v166 offset:6160
	ds_read_b128 v[224:227], v166 offset:10240
	ds_read_b128 v[228:231], v166 offset:10256
	ds_read_b128 v[232:235], v166 offset:14336
	ds_read_b128 v[236:239], v166 offset:14352
	ds_read_b128 v[240:243], v166 offset:18176
	ds_read_b128 v[244:247], v166 offset:18192
	v_add_u32_e32 v167, 0x400, v167
	ds_read2_b32 v[248:249], v167 offset0:0 offset1:8
	s_waitcnt lgkmcnt(12)
; #define LAS __attribute__((address_space(3)))
; template <int CTRL> __device__ __forceinline__ float dpp_f(float x) { return __builtin_bit_cast(float, __builtin_amdgcn_mov_dpp(__builtin_bit_cast(int, x), CTRL, 0xf, 0xf, true)); }
; __device__ __forceinline__ float red8(float d) { d += dpp_f<0xB1>(d); d += dpp_f<0x4E>(d); d += dpp_f<0x141>(d); return d; }
; __device__ __forceinline__ void upd8(V8& S, const V8& w, const V8& b, const V8& k, float sa, float vv) {
;     const f32x2 sa2 = {sa, sa}, vv2 = {vv, vv};
; #pragma unroll
;     for (int i = 0; i < 4; ++i) { f32x2 t = vv2 * k.p[i]; t = sa2 * b.p[i] + t; S.p[i] = S.p[i] * w.p[i] + t; }
; template <int MODE>
; __device__ __forceinline__ void scan_pair(LAS unsigned char* lds, CArgsP a, const ScanUnit u, int nch) {
;     ...
;         for (int t = 0; t < 16; ++t) {
;             const LAS float* p = cb + t * 64 + 8 * ks;
;             const V8 w = ld8(p), kk = ld8(p + 1024), bb = ld8(p + 2048), kv = ld8(p + 3072);
;             const float va = cb[(5 * 16 + t) * 64 + vr0], vb = cb[(5 * 16 + t) * 64 + vr1];
;             float da = dot8(Sa, kk), db = dot8(Sb, kk);
;             da = red8(da); db = red8(db);
;             upd8(Sa, w, bb, kv, -da, va); upd8(Sb, w, bb, kv, -db, vb);
;             if (MODE == 1) {
;                 float pa = dot8(Pa, kk), pb = dot8(Pb, kk);
;                 pa = red8(pa); pb = red8(pb);
;                 updp8(Pa, w, bb, -pa); updp8(Pb, w, bb, -pb);
;             } else {
;                 const V8 rr = ld8(p + 4096);
;                 float ya = dot8(Sa, rr), yb = dot8(Sb, rr);
;                 ya = red8(ya); yb = red8(yb);
;                 if (ks == 0) { Y[t * 64 + vr0] = ya; Y[t * 64 + vr1] = yb; }
;             }
	v_pk_mul_f32 v[40:41], v[12:13], v[112:113]
	v_pk_mul_f32 v[42:43], v[4:5], v[112:113]
	v_pk_mul_f32 v[44:45], v[12:13], v[136:137]
	v_pk_mul_f32 v[46:47], v[4:5], v[136:137]
	v_pk_fma_f32 v[40:41], v[14:15], v[114:115], v[40:41]
	v_pk_fma_f32 v[42:43], v[6:7], v[114:115], v[42:43]
	v_pk_fma_f32 v[44:45], v[14:15], v[138:139], v[44:45]
	v_pk_fma_f32 v[46:47], v[6:7], v[138:139], v[46:47]
	v_pk_fma_f32 v[40:41], v[8:9], v[116:117], v[40:41]
	v_pk_fma_f32 v[42:43], v[0:1], v[116:117], v[42:43]
	v_pk_fma_f32 v[44:45], v[8:9], v[140:141], v[44:45]
	v_pk_fma_f32 v[46:47], v[0:1], v[140:141], v[46:47]
	v_pk_fma_f32 v[40:41], v[10:11], v[118:119], v[40:41]
	v_pk_fma_f32 v[42:43], v[2:3], v[118:119], v[42:43]
	v_pk_fma_f32 v[44:45], v[10:11], v[142:143], v[44:45]
	v_pk_fma_f32 v[46:47], v[2:3], v[142:143], v[46:47]
	v_add_f32_e32 v40, v40, v41
	v_add_f32_e32 v42, v42, v43
	v_add_f32_e32 v44, v44, v45
	v_add_f32_e32 v46, v46, v47
	v_pk_mul_f32 v[88:89], v[128:129], v[98:99] op_sel_hi:[1,0]
	v_pk_mul_f32 v[90:91], v[128:129], v[98:99] op_sel:[0,1] op_sel_hi:[1,1]
	v_pk_mul_f32 v[92:93], v[130:131], v[98:99] op_sel_hi:[1,0]
	v_pk_mul_f32 v[94:95], v[130:131], v[98:99] op_sel:[0,1] op_sel_hi:[1,1]
	v_add_f32_dpp v40, v40, v40 quad_perm:[1,0,3,2] row_mask:0xf bank_mask:0xf bound_ctrl:1
	v_add_f32_dpp v42, v42, v42 quad_perm:[1,0,3,2] row_mask:0xf bank_mask:0xf bound_ctrl:1
	v_add_f32_dpp v44, v44, v44 quad_perm:[1,0,3,2] row_mask:0xf bank_mask:0xf bound_ctrl:1
	v_add_f32_dpp v46, v46, v46 quad_perm:[1,0,3,2] row_mask:0xf bank_mask:0xf bound_ctrl:1
	v_pk_fma_f32 v[12:13], v[12:13], v[104:105], v[88:89]
	v_pk_fma_f32 v[4:5], v[4:5], v[104:105], v[90:91]
	v_pk_fma_f32 v[14:15], v[14:15], v[106:107], v[92:93]
	v_pk_fma_f32 v[6:7], v[6:7], v[106:107], v[94:95]
	v_add_f32_dpp v40, v40, v40 quad_perm:[2,3,0,1] row_mask:0xf bank_mask:0xf bound_ctrl:1
	v_add_f32_dpp v42, v42, v42 quad_perm:[2,3,0,1] row_mask:0xf bank_mask:0xf bound_ctrl:1
	v_add_f32_dpp v44, v44, v44 quad_perm:[2,3,0,1] row_mask:0xf bank_mask:0xf bound_ctrl:1
	v_add_f32_dpp v46, v46, v46 quad_perm:[2,3,0,1] row_mask:0xf bank_mask:0xf bound_ctrl:1
	v_pk_mul_f32 v[88:89], v[132:133], v[98:99] op_sel_hi:[1,0]
	v_pk_mul_f32 v[90:91], v[132:133], v[98:99] op_sel:[0,1] op_sel_hi:[1,1]
	v_pk_mul_f32 v[92:93], v[134:135], v[98:99] op_sel_hi:[1,0]
	v_pk_mul_f32 v[94:95], v[134:135], v[98:99] op_sel:[0,1] op_sel_hi:[1,1]
	v_add_f32_dpp v40, v40, v40 row_half_mirror row_mask:0xf bank_mask:0xf bound_ctrl:1
	v_add_f32_dpp v42, v42, v42 row_half_mirror row_mask:0xf bank_mask:0xf bound_ctrl:1
	v_add_f32_dpp v44, v44, v44 row_half_mirror row_mask:0xf bank_mask:0xf bound_ctrl:1
	v_add_f32_dpp v46, v46, v46 row_half_mirror row_mask:0xf bank_mask:0xf bound_ctrl:1
	v_pk_fma_f32 v[8:9], v[8:9], v[108:109], v[88:89]
	v_pk_fma_f32 v[0:1], v[0:1], v[108:109], v[90:91]
	v_pk_fma_f32 v[10:11], v[10:11], v[110:111], v[92:93]
	v_pk_fma_f32 v[2:3], v[2:3], v[110:111], v[94:95]
	v_pk_fma_f32 v[12:13], v[120:121], v[40:41], v[12:13] op_sel_hi:[1,0,1] neg_lo:[0,1,0] neg_hi:[0,1,0]
	v_pk_fma_f32 v[4:5], v[120:121], v[42:43], v[4:5] op_sel_hi:[1,0,1] neg_lo:[0,1,0] neg_hi:[0,1,0]
	v_pk_fma_f32 v[14:15], v[122:123], v[40:41], v[14:15] op_sel_hi:[1,0,1] neg_lo:[0,1,0] neg_hi:[0,1,0]
	v_pk_fma_f32 v[6:7], v[122:123], v[42:43], v[6:7] op_sel_hi:[1,0,1] neg_lo:[0,1,0] neg_hi:[0,1,0]
	v_pk_fma_f32 v[8:9], v[124:125], v[40:41], v[8:9] op_sel_hi:[1,0,1] neg_lo:[0,1,0] neg_hi:[0,1,0]
	v_pk_fma_f32 v[0:1], v[124:125], v[42:43], v[0:1] op_sel_hi:[1,0,1] neg_lo:[0,1,0] neg_hi:[0,1,0]
	v_pk_fma_f32 v[10:11], v[126:127], v[40:41], v[10:11] op_sel_hi:[1,0,1] neg_lo:[0,1,0] neg_hi:[0,1,0]
	v_pk_fma_f32 v[2:3], v[126:127], v[42:43], v[2:3] op_sel_hi:[1,0,1] neg_lo:[0,1,0] neg_hi:[0,1,0]
	s_and_saveexec_b64 s[42:43], s[6:7]
	ds_write2_b32 v168, v44, v46 offset0:128 offset1:136
	s_mov_b64 exec, s[42:43]
	ds_read_b128 v[104:107], v166 offset:2304
	ds_read_b128 v[108:111], v166 offset:2320
	ds_read_b128 v[112:115], v166 offset:6400
	ds_read_b128 v[116:119], v166 offset:6416
	ds_read_b128 v[120:123], v166 offset:10496
	ds_read_b128 v[124:127], v166 offset:10512
	ds_read_b128 v[128:131], v166 offset:14592
	ds_read_b128 v[132:135], v166 offset:14608
	ds_read_b128 v[136:139], v166 offset:18432
	ds_read_b128 v[140:143], v166 offset:18448
	ds_read2_b32 v[98:99], v167 offset0:64 offset1:72
	s_waitcnt lgkmcnt(12)
; #define LAS __attribute__((address_space(3)))
; template <int CTRL> __device__ __forceinline__ float dpp_f(float x) { return __builtin_bit_cast(float, __builtin_amdgcn_mov_dpp(__builtin_bit_cast(int, x), CTRL, 0xf, 0xf, true)); }
; __device__ __forceinline__ float red8(float d) { d += dpp_f<0xB1>(d); d += dpp_f<0x4E>(d); d += dpp_f<0x141>(d); return d; }
; __device__ __forceinline__ void upd8(V8& S, const V8& w, const V8& b, const V8& k, float sa, float vv) {
;     const f32x2 sa2 = {sa, sa}, vv2 = {vv, vv};
; #pragma unroll
;     for (int i = 0; i < 4; ++i) { f32x2 t = vv2 * k.p[i]; t = sa2 * b.p[i] + t; S.p[i] = S.p[i] * w.p[i] + t; }
; template <int MODE>
; __device__ __forceinline__ void scan_pair(LAS unsigned char* lds, CArgsP a, const ScanUnit u, int nch) {
;     ...
;         for (int t = 0; t < 16; ++t) {
;             const LAS float* p = cb + t * 64 + 8 * ks;
;             const V8 w = ld8(p), kk = ld8(p + 1024), bb = ld8(p + 2048), kv = ld8(p + 3072);
;             const float va = cb[(5 * 16 + t) * 64 + vr0], vb = cb[(5 * 16 + t) * 64 + vr1];
;             float da = dot8(Sa, kk), db = dot8(Sb, kk);
;             da = red8(da); db = red8(db);
;             upd8(Sa, w, bb, kv, -da, va); upd8(Sb, w, bb, kv, -db, vb);
;             if (MODE == 1) {
;                 float pa = dot8(Pa, kk), pb = dot8(Pb, kk);
;                 pa = red8(pa); pb = red8(pb);
;                 updp8(Pa, w, bb, -pa); updp8(Pb, w, bb, -pb);
;             } else {
;                 const V8 rr = ld8(p + 4096);
;                 float ya = dot8(Sa, rr), yb = dot8(Sb, rr);
;                 ya = red8(ya); yb = red8(yb);
;                 if (ks == 0) { Y[t * 64 + vr0] = ya; Y[t * 64 + vr1] = yb; }
;             }
	v_pk_mul_f32 v[40:41], v[12:13], v[216:217]
	v_pk_mul_f32 v[42:43], v[4:5], v[216:217]
	v_pk_mul_f32 v[44:45], v[12:13], v[240:241]
	v_pk_mul_f32 v[46:47], v[4:5], v[240:241]
	v_pk_fma_f32 v[40:41], v[14:15], v[218:219], v[40:41]
	v_pk_fma_f32 v[42:43], v[6:7], v[218:219], v[42:43]
	v_pk_fma_f32 v[44:45], v[14:15], v[242:243], v[44:45]
	v_pk_fma_f32 v[46:47], v[6:7], v[242:243], v[46:47]
	v_pk_fma_f32 v[40:41], v[8:9], v[220:221], v[40:41]
	v_pk_fma_f32 v[42:43], v[0:1], v[220:221], v[42:43]
	v_pk_fma_f32 v[44:45], v[8:9], v[244:245], v[44:45]
	v_pk_fma_f32 v[46:47], v[0:1], v[244:245], v[46:47]
	v_pk_fma_f32 v[40:41], v[10:11], v[222:223], v[40:41]
	v_pk_fma_f32 v[42:43], v[2:3], v[222:223], v[42:43]
	v_pk_fma_f32 v[44:45], v[10:11], v[246:247], v[44:45]
	v_pk_fma_f32 v[46:47], v[2:3], v[246:247], v[46:47]
	v_add_f32_e32 v40, v40, v41
	v_add_f32_e32 v42, v42, v43
	v_add_f32_e32 v44, v44, v45
	v_add_f32_e32 v46, v46, v47
	v_pk_mul_f32 v[88:89], v[232:233], v[248:249] op_sel_hi:[1,0]
	v_pk_mul_f32 v[90:91], v[232:233], v[248:249] op_sel:[0,1] op_sel_hi:[1,1]
	v_pk_mul_f32 v[92:93], v[234:235], v[248:249] op_sel_hi:[1,0]
	v_pk_mul_f32 v[94:95], v[234:235], v[248:249] op_sel:[0,1] op_sel_hi:[1,1]
	v_add_f32_dpp v40, v40, v40 quad_perm:[1,0,3,2] row_mask:0xf bank_mask:0xf bound_ctrl:1
	v_add_f32_dpp v42, v42, v42 quad_perm:[1,0,3,2] row_mask:0xf bank_mask:0xf bound_ctrl:1
	v_add_f32_dpp v44, v44, v44 quad_perm:[1,0,3,2] row_mask:0xf bank_mask:0xf bound_ctrl:1
	v_add_f32_dpp v46, v46, v46 quad_perm:[1,0,3,2] row_mask:0xf bank_mask:0xf bound_ctrl:1
	v_pk_fma_f32 v[12:13], v[12:13], v[208:209], v[88:89]
	v_pk_fma_f32 v[4:5], v[4:5], v[208:209], v[90:91]
	v_pk_fma_f32 v[14:15], v[14:15], v[210:211], v[92:93]
	v_pk_fma_f32 v[6:7], v[6:7], v[210:211], v[94:95]
	v_add_f32_dpp v40, v40, v40 quad_perm:[2,3,0,1] row_mask:0xf bank_mask:0xf bound_ctrl:1
	v_add_f32_dpp v42, v42, v42 quad_perm:[2,3,0,1] row_mask:0xf bank_mask:0xf bound_ctrl:1
	v_add_f32_dpp v44, v44, v44 quad_perm:[2,3,0,1] row_mask:0xf bank_mask:0xf bound_ctrl:1
	v_add_f32_dpp v46, v46, v46 quad_perm:[2,3,0,1] row_mask:0xf bank_mask:0xf bound_ctrl:1
	v_pk_mul_f32 v[88:89], v[236:237], v[248:249] op_sel_hi:[1,0]
	v_pk_mul_f32 v[90:91], v[236:237], v[248:249] op_sel:[0,1] op_sel_hi:[1,1]
	v_pk_mul_f32 v[92:93], v[238:239], v[248:249] op_sel_hi:[1,0]
	v_pk_mul_f32 v[94:95], v[238:239], v[248:249] op_sel:[0,1] op_sel_hi:[1,1]
	v_add_f32_dpp v40, v40, v40 row_half_mirror row_mask:0xf bank_mask:0xf bound_ctrl:1
	v_add_f32_dpp v42, v42, v42 row_half_mirror row_mask:0xf bank_mask:0xf bound_ctrl:1
	v_add_f32_dpp v44, v44, v44 row_half_mirror row_mask:0xf bank_mask:0xf bound_ctrl:1
	v_add_f32_dpp v46, v46, v46 row_half_mirror row_mask:0xf bank_mask:0xf bound_ctrl:1
	v_pk_fma_f32 v[8:9], v[8:9], v[212:213], v[88:89]
	v_pk_fma_f32 v[0:1], v[0:1], v[212:213], v[90:91]
	v_pk_fma_f32 v[10:11], v[10:11], v[214:215], v[92:93]
	v_pk_fma_f32 v[2:3], v[2:3], v[214:215], v[94:95]
	v_pk_fma_f32 v[12:13], v[224:225], v[40:41], v[12:13] op_sel_hi:[1,0,1] neg_lo:[0,1,0] neg_hi:[0,1,0]
	v_pk_fma_f32 v[4:5], v[224:225], v[42:43], v[4:5] op_sel_hi:[1,0,1] neg_lo:[0,1,0] neg_hi:[0,1,0]
	v_pk_fma_f32 v[14:15], v[226:227], v[40:41], v[14:15] op_sel_hi:[1,0,1] neg_lo:[0,1,0] neg_hi:[0,1,0]
	v_pk_fma_f32 v[6:7], v[226:227], v[42:43], v[6:7] op_sel_hi:[1,0,1] neg_lo:[0,1,0] neg_hi:[0,1,0]
	v_pk_fma_f32 v[8:9], v[228:229], v[40:41], v[8:9] op_sel_hi:[1,0,1] neg_lo:[0,1,0] neg_hi:[0,1,0]
	v_pk_fma_f32 v[0:1], v[228:229], v[42:43], v[0:1] op_sel_hi:[1,0,1] neg_lo:[0,1,0] neg_hi:[0,1,0]
	v_pk_fma_f32 v[10:11], v[230:231], v[40:41], v[10:11] op_sel_hi:[1,0,1] neg_lo:[0,1,0] neg_hi:[0,1,0]
	v_pk_fma_f32 v[2:3], v[230:231], v[42:43], v[2:3] op_sel_hi:[1,0,1] neg_lo:[0,1,0] neg_hi:[0,1,0]
	s_and_saveexec_b64 s[42:43], s[6:7]
	ds_write2_b32 v168, v44, v46 offset0:192 offset1:200
	s_mov_b64 exec, s[42:43]
	ds_read_b128 v[208:211], v166 offset:2560
	ds_read_b128 v[212:215], v166 offset:2576
	ds_read_b128 v[216:219], v166 offset:6656
	ds_read_b128 v[220:223], v166 offset:6672
	ds_read_b128 v[224:227], v166 offset:10752
	ds_read_b128 v[228:231], v166 offset:10768
	ds_read_b128 v[232:235], v166 offset:14848
	ds_read_b128 v[236:239], v166 offset:14864
	ds_read_b128 v[240:243], v166 offset:18688
	ds_read_b128 v[244:247], v166 offset:18704
	ds_read2_b32 v[248:249], v167 offset0:128 offset1:136
	s_waitcnt lgkmcnt(12)
; #define LAS __attribute__((address_space(3)))
; template <int CTRL> __device__ __forceinline__ float dpp_f(float x) { return __builtin_bit_cast(float, __builtin_amdgcn_mov_dpp(__builtin_bit_cast(int, x), CTRL, 0xf, 0xf, true)); }
; __device__ __forceinline__ float red8(float d) { d += dpp_f<0xB1>(d); d += dpp_f<0x4E>(d); d += dpp_f<0x141>(d); return d; }
; __device__ __forceinline__ void upd8(V8& S, const V8& w, const V8& b, const V8& k, float sa, float vv) {
;     const f32x2 sa2 = {sa, sa}, vv2 = {vv, vv};
; #pragma unroll
;     for (int i = 0; i < 4; ++i) { f32x2 t = vv2 * k.p[i]; t = sa2 * b.p[i] + t; S.p[i] = S.p[i] * w.p[i] + t; }
; template <int MODE>
; __device__ __forceinline__ void scan_pair(LAS unsigned char* lds, CArgsP a, const ScanUnit u, int nch) {
;     ...
;         for (int t = 0; t < 16; ++t) {
;             const LAS float* p = cb + t * 64 + 8 * ks;
;             const V8 w = ld8(p), kk = ld8(p + 1024), bb = ld8(p + 2048), kv = ld8(p + 3072);
;             const float va = cb[(5 * 16 + t) * 64 + vr0], vb = cb[(5 * 16 + t) * 64 + vr1];
;             float da = dot8(Sa, kk), db = dot8(Sb, kk);
;             da = red8(da); db = red8(db);
;             upd8(Sa, w, bb, kv, -da, va); upd8(Sb, w, bb, kv, -db, vb);
;             if (MODE == 1) {
;                 float pa = dot8(Pa, kk), pb = dot8(Pb, kk);
;                 pa = red8(pa); pb = red8(pb);
;                 updp8(Pa, w, bb, -pa); updp8(Pb, w, bb, -pb);
;             } else {
;                 const V8 rr = ld8(p + 4096);
;                 float ya = dot8(Sa, rr), yb = dot8(Sb, rr);
;                 ya = red8(ya); yb = red8(yb);
;                 if (ks == 0) { Y[t * 64 + vr0] = ya; Y[t * 64 + vr1] = yb; }
;             }
	v_pk_mul_f32 v[40:41], v[12:13], v[112:113]
	v_pk_mul_f32 v[42:43], v[4:5], v[112:113]
	v_pk_mul_f32 v[44:45], v[12:13], v[136:137]
	v_pk_mul_f32 v[46:47], v[4:5], v[136:137]
	v_pk_fma_f32 v[40:41], v[14:15], v[114:115], v[40:41]
	v_pk_fma_f32 v[42:43], v[6:7], v[114:115], v[42:43]
	v_pk_fma_f32 v[44:45], v[14:15], v[138:139], v[44:45]
	v_pk_fma_f32 v[46:47], v[6:7], v[138:139], v[46:47]
	v_pk_fma_f32 v[40:41], v[8:9], v[116:117], v[40:41]
	v_pk_fma_f32 v[42:43], v[0:1], v[116:117], v[42:43]
	v_pk_fma_f32 v[44:45], v[8:9], v[140:141], v[44:45]
	v_pk_fma_f32 v[46:47], v[0:1], v[140:141], v[46:47]
	v_pk_fma_f32 v[40:41], v[10:11], v[118:119], v[40:41]
	v_pk_fma_f32 v[42:43], v[2:3], v[118:119], v[42:43]
	v_pk_fma_f32 v[44:45], v[10:11], v[142:143], v[44:45]
	v_pk_fma_f32 v[46:47], v[2:3], v[142:143], v[46:47]
	v_add_f32_e32 v40, v40, v41
	v_add_f32_e32 v42, v42, v43
	v_add_f32_e32 v44, v44, v45
	v_add_f32_e32 v46, v46, v47
	v_pk_mul_f32 v[88:89], v[128:129], v[98:99] op_sel_hi:[1,0]
	v_pk_mul_f32 v[90:91], v[128:129], v[98:99] op_sel:[0,1] op_sel_hi:[1,1]
	v_pk_mul_f32 v[92:93], v[130:131], v[98:99] op_sel_hi:[1,0]
	v_pk_mul_f32 v[94:95], v[130:131], v[98:99] op_sel:[0,1] op_sel_hi:[1,1]
	v_add_f32_dpp v40, v40, v40 quad_perm:[1,0,3,2] row_mask:0xf bank_mask:0xf bound_ctrl:1
	v_add_f32_dpp v42, v42, v42 quad_perm:[1,0,3,2] row_mask:0xf bank_mask:0xf bound_ctrl:1
	v_add_f32_dpp v44, v44, v44 quad_perm:[1,0,3,2] row_mask:0xf bank_mask:0xf bound_ctrl:1
	v_add_f32_dpp v46, v46, v46 quad_perm:[1,0,3,2] row_mask:0xf bank_mask:0xf bound_ctrl:1
	v_pk_fma_f32 v[12:13], v[12:13], v[104:105], v[88:89]
	v_pk_fma_f32 v[4:5], v[4:5], v[104:105], v[90:91]
	v_pk_fma_f32 v[14:15], v[14:15], v[106:107], v[92:93]
	v_pk_fma_f32 v[6:7], v[6:7], v[106:107], v[94:95]
	v_add_f32_dpp v40, v40, v40 quad_perm:[2,3,0,1] row_mask:0xf bank_mask:0xf bound_ctrl:1
	v_add_f32_dpp v42, v42, v42 quad_perm:[2,3,0,1] row_mask:0xf bank_mask:0xf bound_ctrl:1
	v_add_f32_dpp v44, v44, v44 quad_perm:[2,3,0,1] row_mask:0xf bank_mask:0xf bound_ctrl:1
	v_add_f32_dpp v46, v46, v46 quad_perm:[2,3,0,1] row_mask:0xf bank_mask:0xf bound_ctrl:1
	v_pk_mul_f32 v[88:89], v[132:133], v[98:99] op_sel_hi:[1,0]
	v_pk_mul_f32 v[90:91], v[132:133], v[98:99] op_sel:[0,1] op_sel_hi:[1,1]
	v_pk_mul_f32 v[92:93], v[134:135], v[98:99] op_sel_hi:[1,0]
	v_pk_mul_f32 v[94:95], v[134:135], v[98:99] op_sel:[0,1] op_sel_hi:[1,1]
	v_add_f32_dpp v40, v40, v40 row_half_mirror row_mask:0xf bank_mask:0xf bound_ctrl:1
	v_add_f32_dpp v42, v42, v42 row_half_mirror row_mask:0xf bank_mask:0xf bound_ctrl:1
	v_add_f32_dpp v44, v44, v44 row_half_mirror row_mask:0xf bank_mask:0xf bound_ctrl:1
	v_add_f32_dpp v46, v46, v46 row_half_mirror row_mask:0xf bank_mask:0xf bound_ctrl:1
	v_pk_fma_f32 v[8:9], v[8:9], v[108:109], v[88:89]
	v_pk_fma_f32 v[0:1], v[0:1], v[108:109], v[90:91]
	v_pk_fma_f32 v[10:11], v[10:11], v[110:111], v[92:93]
	v_pk_fma_f32 v[2:3], v[2:3], v[110:111], v[94:95]
	v_pk_fma_f32 v[12:13], v[120:121], v[40:41], v[12:13] op_sel_hi:[1,0,1] neg_lo:[0,1,0] neg_hi:[0,1,0]
	v_pk_fma_f32 v[4:5], v[120:121], v[42:43], v[4:5] op_sel_hi:[1,0,1] neg_lo:[0,1,0] neg_hi:[0,1,0]
	v_pk_fma_f32 v[14:15], v[122:123], v[40:41], v[14:15] op_sel_hi:[1,0,1] neg_lo:[0,1,0] neg_hi:[0,1,0]
	v_pk_fma_f32 v[6:7], v[122:123], v[42:43], v[6:7] op_sel_hi:[1,0,1] neg_lo:[0,1,0] neg_hi:[0,1,0]
	v_pk_fma_f32 v[8:9], v[124:125], v[40:41], v[8:9] op_sel_hi:[1,0,1] neg_lo:[0,1,0] neg_hi:[0,1,0]
	v_pk_fma_f32 v[0:1], v[124:125], v[42:43], v[0:1] op_sel_hi:[1,0,1] neg_lo:[0,1,0] neg_hi:[0,1,0]
	v_pk_fma_f32 v[10:11], v[126:127], v[40:41], v[10:11] op_sel_hi:[1,0,1] neg_lo:[0,1,0] neg_hi:[0,1,0]
	v_pk_fma_f32 v[2:3], v[126:127], v[42:43], v[2:3] op_sel_hi:[1,0,1] neg_lo:[0,1,0] neg_hi:[0,1,0]
	v_add_u32_e32 v168, 0x400, v168
	s_and_saveexec_b64 s[42:43], s[6:7]
	ds_write2_b32 v168, v44, v46 offset0:0 offset1:8
	s_mov_b64 exec, s[42:43]
	ds_read_b128 v[104:107], v166 offset:2816
	ds_read_b128 v[108:111], v166 offset:2832
	ds_read_b128 v[112:115], v166 offset:6912
	ds_read_b128 v[116:119], v166 offset:6928
	ds_read_b128 v[120:123], v166 offset:11008
	ds_read_b128 v[124:127], v166 offset:11024
	ds_read_b128 v[128:131], v166 offset:15104
	ds_read_b128 v[132:135], v166 offset:15120
	ds_read_b128 v[136:139], v166 offset:18944
	ds_read_b128 v[140:143], v166 offset:18960
	ds_read2_b32 v[98:99], v167 offset0:192 offset1:200
	s_waitcnt lgkmcnt(12)
; #define LAS __attribute__((address_space(3)))
; template <int CTRL> __device__ __forceinline__ float dpp_f(float x) { return __builtin_bit_cast(float, __builtin_amdgcn_mov_dpp(__builtin_bit_cast(int, x), CTRL, 0xf, 0xf, true)); }
; __device__ __forceinline__ float red8(float d) { d += dpp_f<0xB1>(d); d += dpp_f<0x4E>(d); d += dpp_f<0x141>(d); return d; }
; __device__ __forceinline__ void upd8(V8& S, const V8& w, const V8& b, const V8& k, float sa, float vv) {
;     const f32x2 sa2 = {sa, sa}, vv2 = {vv, vv};
; #pragma unroll
;     for (int i = 0; i < 4; ++i) { f32x2 t = vv2 * k.p[i]; t = sa2 * b.p[i] + t; S.p[i] = S.p[i] * w.p[i] + t; }
; template <int MODE>
; __device__ __forceinline__ void scan_pair(LAS unsigned char* lds, CArgsP a, const ScanUnit u, int nch) {
;     ...
;         for (int t = 0; t < 16; ++t) {
;             const LAS float* p = cb + t * 64 + 8 * ks;
;             const V8 w = ld8(p), kk = ld8(p + 1024), bb = ld8(p + 2048), kv = ld8(p + 3072);
;             const float va = cb[(5 * 16 + t) * 64 + vr0], vb = cb[(5 * 16 + t) * 64 + vr1];
;             float da = dot8(Sa, kk), db = dot8(Sb, kk);
;             da = red8(da); db = red8(db);
;             upd8(Sa, w, bb, kv, -da, va); upd8(Sb, w, bb, kv, -db, vb);
;             if (MODE == 1) {
;                 float pa = dot8(Pa, kk), pb = dot8(Pb, kk);
;                 pa = red8(pa); pb = red8(pb);
;                 updp8(Pa, w, bb, -pa); updp8(Pb, w, bb, -pb);
;             } else {
;                 const V8 rr = ld8(p + 4096);
;                 float ya = dot8(Sa, rr), yb = dot8(Sb, rr);
;                 ya = red8(ya); yb = red8(yb);
;                 if (ks == 0) { Y[t * 64 + vr0] = ya; Y[t * 64 + vr1] = yb; }
;             }
	v_pk_mul_f32 v[40:41], v[12:13], v[216:217]
	v_pk_mul_f32 v[42:43], v[4:5], v[216:217]
	v_pk_mul_f32 v[44:45], v[12:13], v[240:241]
	v_pk_mul_f32 v[46:47], v[4:5], v[240:241]
	v_pk_fma_f32 v[40:41], v[14:15], v[218:219], v[40:41]
	v_pk_fma_f32 v[42:43], v[6:7], v[218:219], v[42:43]
	v_pk_fma_f32 v[44:45], v[14:15], v[242:243], v[44:45]
	v_pk_fma_f32 v[46:47], v[6:7], v[242:243], v[46:47]
	v_pk_fma_f32 v[40:41], v[8:9], v[220:221], v[40:41]
	v_pk_fma_f32 v[42:43], v[0:1], v[220:221], v[42:43]
	v_pk_fma_f32 v[44:45], v[8:9], v[244:245], v[44:45]
	v_pk_fma_f32 v[46:47], v[0:1], v[244:245], v[46:47]
	v_pk_fma_f32 v[40:41], v[10:11], v[222:223], v[40:41]
	v_pk_fma_f32 v[42:43], v[2:3], v[222:223], v[42:43]
	v_pk_fma_f32 v[44:45], v[10:11], v[246:247], v[44:45]
	v_pk_fma_f32 v[46:47], v[2:3], v[246:247], v[46:47]
	v_add_f32_e32 v40, v40, v41
	v_add_f32_e32 v42, v42, v43
	v_add_f32_e32 v44, v44, v45
	v_add_f32_e32 v46, v46, v47
	v_pk_mul_f32 v[88:89], v[232:233], v[248:249] op_sel_hi:[1,0]
	v_pk_mul_f32 v[90:91], v[232:233], v[248:249] op_sel:[0,1] op_sel_hi:[1,1]
	v_pk_mul_f32 v[92:93], v[234:235], v[248:249] op_sel_hi:[1,0]
	v_pk_mul_f32 v[94:95], v[234:235], v[248:249] op_sel:[0,1] op_sel_hi:[1,1]
	v_add_f32_dpp v40, v40, v40 quad_perm:[1,0,3,2] row_mask:0xf bank_mask:0xf bound_ctrl:1
	v_add_f32_dpp v42, v42, v42 quad_perm:[1,0,3,2] row_mask:0xf bank_mask:0xf bound_ctrl:1
	v_add_f32_dpp v44, v44, v44 quad_perm:[1,0,3,2] row_mask:0xf bank_mask:0xf bound_ctrl:1
	v_add_f32_dpp v46, v46, v46 quad_perm:[1,0,3,2] row_mask:0xf bank_mask:0xf bound_ctrl:1
	v_pk_fma_f32 v[12:13], v[12:13], v[208:209], v[88:89]
	v_pk_fma_f32 v[4:5], v[4:5], v[208:209], v[90:91]
	v_pk_fma_f32 v[14:15], v[14:15], v[210:211], v[92:93]
	v_pk_fma_f32 v[6:7], v[6:7], v[210:211], v[94:95]
	v_add_f32_dpp v40, v40, v40 quad_perm:[2,3,0,1] row_mask:0xf bank_mask:0xf bound_ctrl:1
	v_add_f32_dpp v42, v42, v42 quad_perm:[2,3,0,1] row_mask:0xf bank_mask:0xf bound_ctrl:1
	v_add_f32_dpp v44, v44, v44 quad_perm:[2,3,0,1] row_mask:0xf bank_mask:0xf bound_ctrl:1
	v_add_f32_dpp v46, v46, v46 quad_perm:[2,3,0,1] row_mask:0xf bank_mask:0xf bound_ctrl:1
	v_pk_mul_f32 v[88:89], v[236:237], v[248:249] op_sel_hi:[1,0]
	v_pk_mul_f32 v[90:91], v[236:237], v[248:249] op_sel:[0,1] op_sel_hi:[1,1]
	v_pk_mul_f32 v[92:93], v[238:239], v[248:249] op_sel_hi:[1,0]
	v_pk_mul_f32 v[94:95], v[238:239], v[248:249] op_sel:[0,1] op_sel_hi:[1,1]
	v_add_f32_dpp v40, v40, v40 row_half_mirror row_mask:0xf bank_mask:0xf bound_ctrl:1
	v_add_f32_dpp v42, v42, v42 row_half_mirror row_mask:0xf bank_mask:0xf bound_ctrl:1
	v_add_f32_dpp v44, v44, v44 row_half_mirror row_mask:0xf bank_mask:0xf bound_ctrl:1
	v_add_f32_dpp v46, v46, v46 row_half_mirror row_mask:0xf bank_mask:0xf bound_ctrl:1
	v_pk_fma_f32 v[8:9], v[8:9], v[212:213], v[88:89]
	v_pk_fma_f32 v[0:1], v[0:1], v[212:213], v[90:91]
	v_pk_fma_f32 v[10:11], v[10:11], v[214:215], v[92:93]
	v_pk_fma_f32 v[2:3], v[2:3], v[214:215], v[94:95]
	v_pk_fma_f32 v[12:13], v[224:225], v[40:41], v[12:13] op_sel_hi:[1,0,1] neg_lo:[0,1,0] neg_hi:[0,1,0]
	v_pk_fma_f32 v[4:5], v[224:225], v[42:43], v[4:5] op_sel_hi:[1,0,1] neg_lo:[0,1,0] neg_hi:[0,1,0]
	v_pk_fma_f32 v[14:15], v[226:227], v[40:41], v[14:15] op_sel_hi:[1,0,1] neg_lo:[0,1,0] neg_hi:[0,1,0]
	v_pk_fma_f32 v[6:7], v[226:227], v[42:43], v[6:7] op_sel_hi:[1,0,1] neg_lo:[0,1,0] neg_hi:[0,1,0]
	v_pk_fma_f32 v[8:9], v[228:229], v[40:41], v[8:9] op_sel_hi:[1,0,1] neg_lo:[0,1,0] neg_hi:[0,1,0]
	v_pk_fma_f32 v[0:1], v[228:229], v[42:43], v[0:1] op_sel_hi:[1,0,1] neg_lo:[0,1,0] neg_hi:[0,1,0]
	v_pk_fma_f32 v[10:11], v[230:231], v[40:41], v[10:11] op_sel_hi:[1,0,1] neg_lo:[0,1,0] neg_hi:[0,1,0]
	v_pk_fma_f32 v[2:3], v[230:231], v[42:43], v[2:3] op_sel_hi:[1,0,1] neg_lo:[0,1,0] neg_hi:[0,1,0]
	s_and_saveexec_b64 s[42:43], s[6:7]
	ds_write2_b32 v168, v44, v46 offset0:64 offset1:72
	s_mov_b64 exec, s[42:43]
	ds_read_b128 v[208:211], v166 offset:3072
	ds_read_b128 v[212:215], v166 offset:3088
	ds_read_b128 v[216:219], v166 offset:7168
	ds_read_b128 v[220:223], v166 offset:7184
	ds_read_b128 v[224:227], v166 offset:11264
	ds_read_b128 v[228:231], v166 offset:11280
	ds_read_b128 v[232:235], v166 offset:15360
	ds_read_b128 v[236:239], v166 offset:15376
	ds_read_b128 v[240:243], v166 offset:19200
	ds_read_b128 v[244:247], v166 offset:19216
	v_add_u32_e32 v167, 0x400, v167
	ds_read2_b32 v[248:249], v167 offset0:0 offset1:8
	s_waitcnt lgkmcnt(12)
; #define LAS __attribute__((address_space(3)))
; template <int CTRL> __device__ __forceinline__ float dpp_f(float x) { return __builtin_bit_cast(float, __builtin_amdgcn_mov_dpp(__builtin_bit_cast(int, x), CTRL, 0xf, 0xf, true)); }
; __device__ __forceinline__ float red8(float d) { d += dpp_f<0xB1>(d); d += dpp_f<0x4E>(d); d += dpp_f<0x141>(d); return d; }
; __device__ __forceinline__ void upd8(V8& S, const V8& w, const V8& b, const V8& k, float sa, float vv) {
;     const f32x2 sa2 = {sa, sa}, vv2 = {vv, vv};
; #pragma unroll
;     for (int i = 0; i < 4; ++i) { f32x2 t = vv2 * k.p[i]; t = sa2 * b.p[i] + t; S.p[i] = S.p[i] * w.p[i] + t; }
; template <int MODE>
; __device__ __forceinline__ void scan_pair(LAS unsigned char* lds, CArgsP a, const ScanUnit u, int nch) {
;     ...
;         for (int t = 0; t < 16; ++t) {
;             const LAS float* p = cb + t * 64 + 8 * ks;
;             const V8 w = ld8(p), kk = ld8(p + 1024), bb = ld8(p + 2048), kv = ld8(p + 3072);
;             const float va = cb[(5 * 16 + t) * 64 + vr0], vb = cb[(5 * 16 + t) * 64 + vr1];
;             float da = dot8(Sa, kk), db = dot8(Sb, kk);
;             da = red8(da); db = red8(db);
;             upd8(Sa, w, bb, kv, -da, va); upd8(Sb, w, bb, kv, -db, vb);
;             if (MODE == 1) {
;                 float pa = dot8(Pa, kk), pb = dot8(Pb, kk);
;                 pa = red8(pa); pb = red8(pb);
;                 updp8(Pa, w, bb, -pa); updp8(Pb, w, bb, -pb);
;             } else {
;                 const V8 rr = ld8(p + 4096);
;                 float ya = dot8(Sa, rr), yb = dot8(Sb, rr);
;                 ya = red8(ya); yb = red8(yb);
;                 if (ks == 0) { Y[t * 64 + vr0] = ya; Y[t * 64 + vr1] = yb; }
;             }
	v_pk_mul_f32 v[40:41], v[12:13], v[112:113]
	v_pk_mul_f32 v[42:43], v[4:5], v[112:113]
	v_pk_mul_f32 v[44:45], v[12:13], v[136:137]
	v_pk_mul_f32 v[46:47], v[4:5], v[136:137]
	v_pk_fma_f32 v[40:41], v[14:15], v[114:115], v[40:41]
	v_pk_fma_f32 v[42:43], v[6:7], v[114:115], v[42:43]
	v_pk_fma_f32 v[44:45], v[14:15], v[138:139], v[44:45]
	v_pk_fma_f32 v[46:47], v[6:7], v[138:139], v[46:47]
	v_pk_fma_f32 v[40:41], v[8:9], v[116:117], v[40:41]
	v_pk_fma_f32 v[42:43], v[0:1], v[116:117], v[42:43]
	v_pk_fma_f32 v[44:45], v[8:9], v[140:141], v[44:45]
	v_pk_fma_f32 v[46:47], v[0:1], v[140:141], v[46:47]
	v_pk_fma_f32 v[40:41], v[10:11], v[118:119], v[40:41]
	v_pk_fma_f32 v[42:43], v[2:3], v[118:119], v[42:43]
	v_pk_fma_f32 v[44:45], v[10:11], v[142:143], v[44:45]
	v_pk_fma_f32 v[46:47], v[2:3], v[142:143], v[46:47]
	v_add_f32_e32 v40, v40, v41
	v_add_f32_e32 v42, v42, v43
	v_add_f32_e32 v44, v44, v45
	v_add_f32_e32 v46, v46, v47
	v_pk_mul_f32 v[88:89], v[128:129], v[98:99] op_sel_hi:[1,0]
	v_pk_mul_f32 v[90:91], v[128:129], v[98:99] op_sel:[0,1] op_sel_hi:[1,1]
	v_pk_mul_f32 v[92:93], v[130:131], v[98:99] op_sel_hi:[1,0]
	v_pk_mul_f32 v[94:95], v[130:131], v[98:99] op_sel:[0,1] op_sel_hi:[1,1]
	v_add_f32_dpp v40, v40, v40 quad_perm:[1,0,3,2] row_mask:0xf bank_mask:0xf bound_ctrl:1
	v_add_f32_dpp v42, v42, v42 quad_perm:[1,0,3,2] row_mask:0xf bank_mask:0xf bound_ctrl:1
	v_add_f32_dpp v44, v44, v44 quad_perm:[1,0,3,2] row_mask:0xf bank_mask:0xf bound_ctrl:1
	v_add_f32_dpp v46, v46, v46 quad_perm:[1,0,3,2] row_mask:0xf bank_mask:0xf bound_ctrl:1
	v_pk_fma_f32 v[12:13], v[12:13], v[104:105], v[88:89]
	v_pk_fma_f32 v[4:5], v[4:5], v[104:105], v[90:91]
	v_pk_fma_f32 v[14:15], v[14:15], v[106:107], v[92:93]
	v_pk_fma_f32 v[6:7], v[6:7], v[106:107], v[94:95]
	v_add_f32_dpp v40, v40, v40 quad_perm:[2,3,0,1] row_mask:0xf bank_mask:0xf bound_ctrl:1
	v_add_f32_dpp v42, v42, v42 quad_perm:[2,3,0,1] row_mask:0xf bank_mask:0xf bound_ctrl:1
	v_add_f32_dpp v44, v44, v44 quad_perm:[2,3,0,1] row_mask:0xf bank_mask:0xf bound_ctrl:1
	v_add_f32_dpp v46, v46, v46 quad_perm:[2,3,0,1] row_mask:0xf bank_mask:0xf bound_ctrl:1
	v_pk_mul_f32 v[88:89], v[132:133], v[98:99] op_sel_hi:[1,0]
	v_pk_mul_f32 v[90:91], v[132:133], v[98:99] op_sel:[0,1] op_sel_hi:[1,1]
	v_pk_mul_f32 v[92:93], v[134:135], v[98:99] op_sel_hi:[1,0]
	v_pk_mul_f32 v[94:95], v[134:135], v[98:99] op_sel:[0,1] op_sel_hi:[1,1]
	v_add_f32_dpp v40, v40, v40 row_half_mirror row_mask:0xf bank_mask:0xf bound_ctrl:1
	v_add_f32_dpp v42, v42, v42 row_half_mirror row_mask:0xf bank_mask:0xf bound_ctrl:1
	v_add_f32_dpp v44, v44, v44 row_half_mirror row_mask:0xf bank_mask:0xf bound_ctrl:1
	v_add_f32_dpp v46, v46, v46 row_half_mirror row_mask:0xf bank_mask:0xf bound_ctrl:1
	v_pk_fma_f32 v[8:9], v[8:9], v[108:109], v[88:89]
	v_pk_fma_f32 v[0:1], v[0:1], v[108:109], v[90:91]
	v_pk_fma_f32 v[10:11], v[10:11], v[110:111], v[92:93]
	v_pk_fma_f32 v[2:3], v[2:3], v[110:111], v[94:95]
	v_pk_fma_f32 v[12:13], v[120:121], v[40:41], v[12:13] op_sel_hi:[1,0,1] neg_lo:[0,1,0] neg_hi:[0,1,0]
	v_pk_fma_f32 v[4:5], v[120:121], v[42:43], v[4:5] op_sel_hi:[1,0,1] neg_lo:[0,1,0] neg_hi:[0,1,0]
	v_pk_fma_f32 v[14:15], v[122:123], v[40:41], v[14:15] op_sel_hi:[1,0,1] neg_lo:[0,1,0] neg_hi:[0,1,0]
	v_pk_fma_f32 v[6:7], v[122:123], v[42:43], v[6:7] op_sel_hi:[1,0,1] neg_lo:[0,1,0] neg_hi:[0,1,0]
	v_pk_fma_f32 v[8:9], v[124:125], v[40:41], v[8:9] op_sel_hi:[1,0,1] neg_lo:[0,1,0] neg_hi:[0,1,0]
	v_pk_fma_f32 v[0:1], v[124:125], v[42:43], v[0:1] op_sel_hi:[1,0,1] neg_lo:[0,1,0] neg_hi:[0,1,0]
	v_pk_fma_f32 v[10:11], v[126:127], v[40:41], v[10:11] op_sel_hi:[1,0,1] neg_lo:[0,1,0] neg_hi:[0,1,0]
	v_pk_fma_f32 v[2:3], v[126:127], v[42:43], v[2:3] op_sel_hi:[1,0,1] neg_lo:[0,1,0] neg_hi:[0,1,0]
	s_and_saveexec_b64 s[42:43], s[6:7]
	ds_write2_b32 v168, v44, v46 offset0:128 offset1:136
	s_mov_b64 exec, s[42:43]
	ds_read_b128 v[104:107], v166 offset:3328
	ds_read_b128 v[108:111], v166 offset:3344
	ds_read_b128 v[112:115], v166 offset:7424
	ds_read_b128 v[116:119], v166 offset:7440
	ds_read_b128 v[120:123], v166 offset:11520
	ds_read_b128 v[124:127], v166 offset:11536
	ds_read_b128 v[128:131], v166 offset:15616
	ds_read_b128 v[132:135], v166 offset:15632
	ds_read_b128 v[136:139], v166 offset:19456
	ds_read_b128 v[140:143], v166 offset:19472
	ds_read2_b32 v[98:99], v167 offset0:64 offset1:72
	s_waitcnt lgkmcnt(12)
; #define LAS __attribute__((address_space(3)))
; template <int CTRL> __device__ __forceinline__ float dpp_f(float x) { return __builtin_bit_cast(float, __builtin_amdgcn_mov_dpp(__builtin_bit_cast(int, x), CTRL, 0xf, 0xf, true)); }
; __device__ __forceinline__ float red8(float d) { d += dpp_f<0xB1>(d); d += dpp_f<0x4E>(d); d += dpp_f<0x141>(d); return d; }
; __device__ __forceinline__ void upd8(V8& S, const V8& w, const V8& b, const V8& k, float sa, float vv) {
;     const f32x2 sa2 = {sa, sa}, vv2 = {vv, vv};
; #pragma unroll
;     for (int i = 0; i < 4; ++i) { f32x2 t = vv2 * k.p[i]; t = sa2 * b.p[i] + t; S.p[i] = S.p[i] * w.p[i] + t; }
; template <int MODE>
; __device__ __forceinline__ void scan_pair(LAS unsigned char* lds, CArgsP a, const ScanUnit u, int nch) {
;     ...
;         for (int t = 0; t < 16; ++t) {
;             const LAS float* p = cb + t * 64 + 8 * ks;
;             const V8 w = ld8(p), kk = ld8(p + 1024), bb = ld8(p + 2048), kv = ld8(p + 3072);
;             const float va = cb[(5 * 16 + t) * 64 + vr0], vb = cb[(5 * 16 + t) * 64 + vr1];
;             float da = dot8(Sa, kk), db = dot8(Sb, kk);
;             da = red8(da); db = red8(db);
;             upd8(Sa, w, bb, kv, -da, va); upd8(Sb, w, bb, kv, -db, vb);
;             if (MODE == 1) {
;                 float pa = dot8(Pa, kk), pb = dot8(Pb, kk);
;                 pa = red8(pa); pb = red8(pb);
;                 updp8(Pa, w, bb, -pa); updp8(Pb, w, bb, -pb);
;             } else {
;                 const V8 rr = ld8(p + 4096);
;                 float ya = dot8(Sa, rr), yb = dot8(Sb, rr);
;                 ya = red8(ya); yb = red8(yb);
;                 if (ks == 0) { Y[t * 64 + vr0] = ya; Y[t * 64 + vr1] = yb; }
;             }
	v_pk_mul_f32 v[40:41], v[12:13], v[216:217]
	v_pk_mul_f32 v[42:43], v[4:5], v[216:217]
	v_pk_mul_f32 v[44:45], v[12:13], v[240:241]
	v_pk_mul_f32 v[46:47], v[4:5], v[240:241]
	v_pk_fma_f32 v[40:41], v[14:15], v[218:219], v[40:41]
	v_pk_fma_f32 v[42:43], v[6:7], v[218:219], v[42:43]
	v_pk_fma_f32 v[44:45], v[14:15], v[242:243], v[44:45]
	v_pk_fma_f32 v[46:47], v[6:7], v[242:243], v[46:47]
	v_pk_fma_f32 v[40:41], v[8:9], v[220:221], v[40:41]
	v_pk_fma_f32 v[42:43], v[0:1], v[220:221], v[42:43]
	v_pk_fma_f32 v[44:45], v[8:9], v[244:245], v[44:45]
	v_pk_fma_f32 v[46:47], v[0:1], v[244:245], v[46:47]
	v_pk_fma_f32 v[40:41], v[10:11], v[222:223], v[40:41]
	v_pk_fma_f32 v[42:43], v[2:3], v[222:223], v[42:43]
	v_pk_fma_f32 v[44:45], v[10:11], v[246:247], v[44:45]
	v_pk_fma_f32 v[46:47], v[2:3], v[246:247], v[46:47]
	v_add_f32_e32 v40, v40, v41
	v_add_f32_e32 v42, v42, v43
	v_add_f32_e32 v44, v44, v45
	v_add_f32_e32 v46, v46, v47
	v_pk_mul_f32 v[88:89], v[232:233], v[248:249] op_sel_hi:[1,0]
	v_pk_mul_f32 v[90:91], v[232:233], v[248:249] op_sel:[0,1] op_sel_hi:[1,1]
	v_pk_mul_f32 v[92:93], v[234:235], v[248:249] op_sel_hi:[1,0]
	v_pk_mul_f32 v[94:95], v[234:235], v[248:249] op_sel:[0,1] op_sel_hi:[1,1]
	v_add_f32_dpp v40, v40, v40 quad_perm:[1,0,3,2] row_mask:0xf bank_mask:0xf bound_ctrl:1
	v_add_f32_dpp v42, v42, v42 quad_perm:[1,0,3,2] row_mask:0xf bank_mask:0xf bound_ctrl:1
	v_add_f32_dpp v44, v44, v44 quad_perm:[1,0,3,2] row_mask:0xf bank_mask:0xf bound_ctrl:1
	v_add_f32_dpp v46, v46, v46 quad_perm:[1,0,3,2] row_mask:0xf bank_mask:0xf bound_ctrl:1
	v_pk_fma_f32 v[12:13], v[12:13], v[208:209], v[88:89]
	v_pk_fma_f32 v[4:5], v[4:5], v[208:209], v[90:91]
	v_pk_fma_f32 v[14:15], v[14:15], v[210:211], v[92:93]
	v_pk_fma_f32 v[6:7], v[6:7], v[210:211], v[94:95]
	v_add_f32_dpp v40, v40, v40 quad_perm:[2,3,0,1] row_mask:0xf bank_mask:0xf bound_ctrl:1
	v_add_f32_dpp v42, v42, v42 quad_perm:[2,3,0,1] row_mask:0xf bank_mask:0xf bound_ctrl:1
	v_add_f32_dpp v44, v44, v44 quad_perm:[2,3,0,1] row_mask:0xf bank_mask:0xf bound_ctrl:1
	v_add_f32_dpp v46, v46, v46 quad_perm:[2,3,0,1] row_mask:0xf bank_mask:0xf bound_ctrl:1
	v_pk_mul_f32 v[88:89], v[236:237], v[248:249] op_sel_hi:[1,0]
	v_pk_mul_f32 v[90:91], v[236:237], v[248:249] op_sel:[0,1] op_sel_hi:[1,1]
	v_pk_mul_f32 v[92:93], v[238:239], v[248:249] op_sel_hi:[1,0]
	v_pk_mul_f32 v[94:95], v[238:239], v[248:249] op_sel:[0,1] op_sel_hi:[1,1]
	v_add_f32_dpp v40, v40, v40 row_half_mirror row_mask:0xf bank_mask:0xf bound_ctrl:1
	v_add_f32_dpp v42, v42, v42 row_half_mirror row_mask:0xf bank_mask:0xf bound_ctrl:1
	v_add_f32_dpp v44, v44, v44 row_half_mirror row_mask:0xf bank_mask:0xf bound_ctrl:1
	v_add_f32_dpp v46, v46, v46 row_half_mirror row_mask:0xf bank_mask:0xf bound_ctrl:1
	v_pk_fma_f32 v[8:9], v[8:9], v[212:213], v[88:89]
	v_pk_fma_f32 v[0:1], v[0:1], v[212:213], v[90:91]
	v_pk_fma_f32 v[10:11], v[10:11], v[214:215], v[92:93]
	v_pk_fma_f32 v[2:3], v[2:3], v[214:215], v[94:95]
	v_pk_fma_f32 v[12:13], v[224:225], v[40:41], v[12:13] op_sel_hi:[1,0,1] neg_lo:[0,1,0] neg_hi:[0,1,0]
	v_pk_fma_f32 v[4:5], v[224:225], v[42:43], v[4:5] op_sel_hi:[1,0,1] neg_lo:[0,1,0] neg_hi:[0,1,0]
	v_pk_fma_f32 v[14:15], v[226:227], v[40:41], v[14:15] op_sel_hi:[1,0,1] neg_lo:[0,1,0] neg_hi:[0,1,0]
	v_pk_fma_f32 v[6:7], v[226:227], v[42:43], v[6:7] op_sel_hi:[1,0,1] neg_lo:[0,1,0] neg_hi:[0,1,0]
	v_pk_fma_f32 v[8:9], v[228:229], v[40:41], v[8:9] op_sel_hi:[1,0,1] neg_lo:[0,1,0] neg_hi:[0,1,0]
	v_pk_fma_f32 v[0:1], v[228:229], v[42:43], v[0:1] op_sel_hi:[1,0,1] neg_lo:[0,1,0] neg_hi:[0,1,0]
	v_pk_fma_f32 v[10:11], v[230:231], v[40:41], v[10:11] op_sel_hi:[1,0,1] neg_lo:[0,1,0] neg_hi:[0,1,0]
	v_pk_fma_f32 v[2:3], v[230:231], v[42:43], v[2:3] op_sel_hi:[1,0,1] neg_lo:[0,1,0] neg_hi:[0,1,0]
	s_and_saveexec_b64 s[42:43], s[6:7]
	ds_write2_b32 v168, v44, v46 offset0:192 offset1:200
	s_mov_b64 exec, s[42:43]
	ds_read_b128 v[208:211], v166 offset:3584
	ds_read_b128 v[212:215], v166 offset:3600
	ds_read_b128 v[216:219], v166 offset:7680
	ds_read_b128 v[220:223], v166 offset:7696
	ds_read_b128 v[224:227], v166 offset:11776
	ds_read_b128 v[228:231], v166 offset:11792
	ds_read_b128 v[232:235], v166 offset:15872
	ds_read_b128 v[236:239], v166 offset:15888
	ds_read_b128 v[240:243], v166 offset:19712
	ds_read_b128 v[244:247], v166 offset:19728
	ds_read2_b32 v[248:249], v167 offset0:128 offset1:136
	s_waitcnt lgkmcnt(12)
; #define LAS __attribute__((address_space(3)))
; template <int CTRL> __device__ __forceinline__ float dpp_f(float x) { return __builtin_bit_cast(float, __builtin_amdgcn_mov_dpp(__builtin_bit_cast(int, x), CTRL, 0xf, 0xf, true)); }
; __device__ __forceinline__ float red8(float d) { d += dpp_f<0xB1>(d); d += dpp_f<0x4E>(d); d += dpp_f<0x141>(d); return d; }
; __device__ __forceinline__ void upd8(V8& S, const V8& w, const V8& b, const V8& k, float sa, float vv) {
;     const f32x2 sa2 = {sa, sa}, vv2 = {vv, vv};
; #pragma unroll
;     for (int i = 0; i < 4; ++i) { f32x2 t = vv2 * k.p[i]; t = sa2 * b.p[i] + t; S.p[i] = S.p[i] * w.p[i] + t; }
; template <int MODE>
; __device__ __forceinline__ void scan_pair(LAS unsigned char* lds, CArgsP a, const ScanUnit u, int nch) {
;     ...
;         for (int t = 0; t < 16; ++t) {
;             const LAS float* p = cb + t * 64 + 8 * ks;
;             const V8 w = ld8(p), kk = ld8(p + 1024), bb = ld8(p + 2048), kv = ld8(p + 3072);
;             const float va = cb[(5 * 16 + t) * 64 + vr0], vb = cb[(5 * 16 + t) * 64 + vr1];
;             float da = dot8(Sa, kk), db = dot8(Sb, kk);
;             da = red8(da); db = red8(db);
;             upd8(Sa, w, bb, kv, -da, va); upd8(Sb, w, bb, kv, -db, vb);
;             if (MODE == 1) {
;                 float pa = dot8(Pa, kk), pb = dot8(Pb, kk);
;                 pa = red8(pa); pb = red8(pb);
;                 updp8(Pa, w, bb, -pa); updp8(Pb, w, bb, -pb);
;             } else {
;                 const V8 rr = ld8(p + 4096);
;                 float ya = dot8(Sa, rr), yb = dot8(Sb, rr);
;                 ya = red8(ya); yb = red8(yb);
;                 if (ks == 0) { Y[t * 64 + vr0] = ya; Y[t * 64 + vr1] = yb; }
;             }
	v_pk_mul_f32 v[40:41], v[12:13], v[112:113]
	v_pk_mul_f32 v[42:43], v[4:5], v[112:113]
	v_pk_mul_f32 v[44:45], v[12:13], v[136:137]
	v_pk_mul_f32 v[46:47], v[4:5], v[136:137]
	v_pk_fma_f32 v[40:41], v[14:15], v[114:115], v[40:41]
	v_pk_fma_f32 v[42:43], v[6:7], v[114:115], v[42:43]
	v_pk_fma_f32 v[44:45], v[14:15], v[138:139], v[44:45]
	v_pk_fma_f32 v[46:47], v[6:7], v[138:139], v[46:47]
	v_pk_fma_f32 v[40:41], v[8:9], v[116:117], v[40:41]
	v_pk_fma_f32 v[42:43], v[0:1], v[116:117], v[42:43]
	v_pk_fma_f32 v[44:45], v[8:9], v[140:141], v[44:45]
	v_pk_fma_f32 v[46:47], v[0:1], v[140:141], v[46:47]
	v_pk_fma_f32 v[40:41], v[10:11], v[118:119], v[40:41]
	v_pk_fma_f32 v[42:43], v[2:3], v[118:119], v[42:43]
	v_pk_fma_f32 v[44:45], v[10:11], v[142:143], v[44:45]
	v_pk_fma_f32 v[46:47], v[2:3], v[142:143], v[46:47]
	v_add_f32_e32 v40, v40, v41
	v_add_f32_e32 v42, v42, v43
	v_add_f32_e32 v44, v44, v45
	v_add_f32_e32 v46, v46, v47
	v_pk_mul_f32 v[88:89], v[128:129], v[98:99] op_sel_hi:[1,0]
	v_pk_mul_f32 v[90:91], v[128:129], v[98:99] op_sel:[0,1] op_sel_hi:[1,1]
	v_pk_mul_f32 v[92:93], v[130:131], v[98:99] op_sel_hi:[1,0]
	v_pk_mul_f32 v[94:95], v[130:131], v[98:99] op_sel:[0,1] op_sel_hi:[1,1]
	v_add_f32_dpp v40, v40, v40 quad_perm:[1,0,3,2] row_mask:0xf bank_mask:0xf bound_ctrl:1
	v_add_f32_dpp v42, v42, v42 quad_perm:[1,0,3,2] row_mask:0xf bank_mask:0xf bound_ctrl:1
	v_add_f32_dpp v44, v44, v44 quad_perm:[1,0,3,2] row_mask:0xf bank_mask:0xf bound_ctrl:1
	v_add_f32_dpp v46, v46, v46 quad_perm:[1,0,3,2] row_mask:0xf bank_mask:0xf bound_ctrl:1
	v_pk_fma_f32 v[12:13], v[12:13], v[104:105], v[88:89]
	v_pk_fma_f32 v[4:5], v[4:5], v[104:105], v[90:91]
	v_pk_fma_f32 v[14:15], v[14:15], v[106:107], v[92:93]
	v_pk_fma_f32 v[6:7], v[6:7], v[106:107], v[94:95]
	v_add_f32_dpp v40, v40, v40 quad_perm:[2,3,0,1] row_mask:0xf bank_mask:0xf bound_ctrl:1
	v_add_f32_dpp v42, v42, v42 quad_perm:[2,3,0,1] row_mask:0xf bank_mask:0xf bound_ctrl:1
	v_add_f32_dpp v44, v44, v44 quad_perm:[2,3,0,1] row_mask:0xf bank_mask:0xf bound_ctrl:1
	v_add_f32_dpp v46, v46, v46 quad_perm:[2,3,0,1] row_mask:0xf bank_mask:0xf bound_ctrl:1
	v_pk_mul_f32 v[88:89], v[132:133], v[98:99] op_sel_hi:[1,0]
	v_pk_mul_f32 v[90:91], v[132:133], v[98:99] op_sel:[0,1] op_sel_hi:[1,1]
	v_pk_mul_f32 v[92:93], v[134:135], v[98:99] op_sel_hi:[1,0]
	v_pk_mul_f32 v[94:95], v[134:135], v[98:99] op_sel:[0,1] op_sel_hi:[1,1]
	v_add_f32_dpp v40, v40, v40 row_half_mirror row_mask:0xf bank_mask:0xf bound_ctrl:1
	v_add_f32_dpp v42, v42, v42 row_half_mirror row_mask:0xf bank_mask:0xf bound_ctrl:1
	v_add_f32_dpp v44, v44, v44 row_half_mirror row_mask:0xf bank_mask:0xf bound_ctrl:1
	v_add_f32_dpp v46, v46, v46 row_half_mirror row_mask:0xf bank_mask:0xf bound_ctrl:1
	v_pk_fma_f32 v[8:9], v[8:9], v[108:109], v[88:89]
	v_pk_fma_f32 v[0:1], v[0:1], v[108:109], v[90:91]
	v_pk_fma_f32 v[10:11], v[10:11], v[110:111], v[92:93]
	v_pk_fma_f32 v[2:3], v[2:3], v[110:111], v[94:95]
	v_pk_fma_f32 v[12:13], v[120:121], v[40:41], v[12:13] op_sel_hi:[1,0,1] neg_lo:[0,1,0] neg_hi:[0,1,0]
	v_pk_fma_f32 v[4:5], v[120:121], v[42:43], v[4:5] op_sel_hi:[1,0,1] neg_lo:[0,1,0] neg_hi:[0,1,0]
	v_pk_fma_f32 v[14:15], v[122:123], v[40:41], v[14:15] op_sel_hi:[1,0,1] neg_lo:[0,1,0] neg_hi:[0,1,0]
	v_pk_fma_f32 v[6:7], v[122:123], v[42:43], v[6:7] op_sel_hi:[1,0,1] neg_lo:[0,1,0] neg_hi:[0,1,0]
	v_pk_fma_f32 v[8:9], v[124:125], v[40:41], v[8:9] op_sel_hi:[1,0,1] neg_lo:[0,1,0] neg_hi:[0,1,0]
	v_pk_fma_f32 v[0:1], v[124:125], v[42:43], v[0:1] op_sel_hi:[1,0,1] neg_lo:[0,1,0] neg_hi:[0,1,0]
	v_pk_fma_f32 v[10:11], v[126:127], v[40:41], v[10:11] op_sel_hi:[1,0,1] neg_lo:[0,1,0] neg_hi:[0,1,0]
	v_pk_fma_f32 v[2:3], v[126:127], v[42:43], v[2:3] op_sel_hi:[1,0,1] neg_lo:[0,1,0] neg_hi:[0,1,0]
	v_add_u32_e32 v168, 0x400, v168
	s_and_saveexec_b64 s[42:43], s[6:7]
	ds_write2_b32 v168, v44, v46 offset0:0 offset1:8
	s_mov_b64 exec, s[42:43]
	ds_read_b128 v[104:107], v166 offset:3840
	ds_read_b128 v[108:111], v166 offset:3856
	ds_read_b128 v[112:115], v166 offset:7936
	ds_read_b128 v[116:119], v166 offset:7952
	ds_read_b128 v[120:123], v166 offset:12032
	ds_read_b128 v[124:127], v166 offset:12048
	ds_read_b128 v[128:131], v166 offset:16128
	ds_read_b128 v[132:135], v166 offset:16144
	ds_read_b128 v[136:139], v166 offset:19968
	ds_read_b128 v[140:143], v166 offset:19984
	ds_read2_b32 v[98:99], v167 offset0:192 offset1:200
	s_waitcnt lgkmcnt(12)
; #define LAS __attribute__((address_space(3)))
; template <int CTRL> __device__ __forceinline__ float dpp_f(float x) { return __builtin_bit_cast(float, __builtin_amdgcn_mov_dpp(__builtin_bit_cast(int, x), CTRL, 0xf, 0xf, true)); }
; __device__ __forceinline__ float red8(float d) { d += dpp_f<0xB1>(d); d += dpp_f<0x4E>(d); d += dpp_f<0x141>(d); return d; }
; __device__ __forceinline__ void upd8(V8& S, const V8& w, const V8& b, const V8& k, float sa, float vv) {
;     const f32x2 sa2 = {sa, sa}, vv2 = {vv, vv};
; #pragma unroll
;     for (int i = 0; i < 4; ++i) { f32x2 t = vv2 * k.p[i]; t = sa2 * b.p[i] + t; S.p[i] = S.p[i] * w.p[i] + t; }
; template <int MODE>
; __device__ __forceinline__ void scan_pair(LAS unsigned char* lds, CArgsP a, const ScanUnit u, int nch) {
;     ...
;         for (int t = 0; t < 16; ++t) {
;             const LAS float* p = cb + t * 64 + 8 * ks;
;             const V8 w = ld8(p), kk = ld8(p + 1024), bb = ld8(p + 2048), kv = ld8(p + 3072);
;             const float va = cb[(5 * 16 + t) * 64 + vr0], vb = cb[(5 * 16 + t) * 64 + vr1];
;             float da = dot8(Sa, kk), db = dot8(Sb, kk);
;             da = red8(da); db = red8(db);
;             upd8(Sa, w, bb, kv, -da, va); upd8(Sb, w, bb, kv, -db, vb);
;             if (MODE == 1) {
;                 float pa = dot8(Pa, kk), pb = dot8(Pb, kk);
;                 pa = red8(pa); pb = red8(pb);
;                 updp8(Pa, w, bb, -pa); updp8(Pb, w, bb, -pb);
;             } else {
;                 const V8 rr = ld8(p + 4096);
;                 float ya = dot8(Sa, rr), yb = dot8(Sb, rr);
;                 ya = red8(ya); yb = red8(yb);
;                 if (ks == 0) { Y[t * 64 + vr0] = ya; Y[t * 64 + vr1] = yb; }
;             }
	v_pk_mul_f32 v[40:41], v[12:13], v[216:217]
	v_pk_mul_f32 v[42:43], v[4:5], v[216:217]
	v_pk_mul_f32 v[44:45], v[12:13], v[240:241]
	v_pk_mul_f32 v[46:47], v[4:5], v[240:241]
	v_pk_fma_f32 v[40:41], v[14:15], v[218:219], v[40:41]
	v_pk_fma_f32 v[42:43], v[6:7], v[218:219], v[42:43]
	v_pk_fma_f32 v[44:45], v[14:15], v[242:243], v[44:45]
	v_pk_fma_f32 v[46:47], v[6:7], v[242:243], v[46:47]
	v_pk_fma_f32 v[40:41], v[8:9], v[220:221], v[40:41]
	v_pk_fma_f32 v[42:43], v[0:1], v[220:221], v[42:43]
	v_pk_fma_f32 v[44:45], v[8:9], v[244:245], v[44:45]
	v_pk_fma_f32 v[46:47], v[0:1], v[244:245], v[46:47]
	v_pk_fma_f32 v[40:41], v[10:11], v[222:223], v[40:41]
	v_pk_fma_f32 v[42:43], v[2:3], v[222:223], v[42:43]
	v_pk_fma_f32 v[44:45], v[10:11], v[246:247], v[44:45]
	v_pk_fma_f32 v[46:47], v[2:3], v[246:247], v[46:47]
	v_add_f32_e32 v40, v40, v41
	v_add_f32_e32 v42, v42, v43
	v_add_f32_e32 v44, v44, v45
	v_add_f32_e32 v46, v46, v47
	v_pk_mul_f32 v[88:89], v[232:233], v[248:249] op_sel_hi:[1,0]
	v_pk_mul_f32 v[90:91], v[232:233], v[248:249] op_sel:[0,1] op_sel_hi:[1,1]
	v_pk_mul_f32 v[92:93], v[234:235], v[248:249] op_sel_hi:[1,0]
	v_pk_mul_f32 v[94:95], v[234:235], v[248:249] op_sel:[0,1] op_sel_hi:[1,1]
	v_add_f32_dpp v40, v40, v40 quad_perm:[1,0,3,2] row_mask:0xf bank_mask:0xf bound_ctrl:1
	v_add_f32_dpp v42, v42, v42 quad_perm:[1,0,3,2] row_mask:0xf bank_mask:0xf bound_ctrl:1
	v_add_f32_dpp v44, v44, v44 quad_perm:[1,0,3,2] row_mask:0xf bank_mask:0xf bound_ctrl:1
	v_add_f32_dpp v46, v46, v46 quad_perm:[1,0,3,2] row_mask:0xf bank_mask:0xf bound_ctrl:1
	v_pk_fma_f32 v[12:13], v[12:13], v[208:209], v[88:89]
	v_pk_fma_f32 v[4:5], v[4:5], v[208:209], v[90:91]
	v_pk_fma_f32 v[14:15], v[14:15], v[210:211], v[92:93]
	v_pk_fma_f32 v[6:7], v[6:7], v[210:211], v[94:95]
	v_add_f32_dpp v40, v40, v40 quad_perm:[2,3,0,1] row_mask:0xf bank_mask:0xf bound_ctrl:1
	v_add_f32_dpp v42, v42, v42 quad_perm:[2,3,0,1] row_mask:0xf bank_mask:0xf bound_ctrl:1
	v_add_f32_dpp v44, v44, v44 quad_perm:[2,3,0,1] row_mask:0xf bank_mask:0xf bound_ctrl:1
	v_add_f32_dpp v46, v46, v46 quad_perm:[2,3,0,1] row_mask:0xf bank_mask:0xf bound_ctrl:1
	v_pk_mul_f32 v[88:89], v[236:237], v[248:249] op_sel_hi:[1,0]
	v_pk_mul_f32 v[90:91], v[236:237], v[248:249] op_sel:[0,1] op_sel_hi:[1,1]
	v_pk_mul_f32 v[92:93], v[238:239], v[248:249] op_sel_hi:[1,0]
	v_pk_mul_f32 v[94:95], v[238:239], v[248:249] op_sel:[0,1] op_sel_hi:[1,1]
	v_add_f32_dpp v40, v40, v40 row_half_mirror row_mask:0xf bank_mask:0xf bound_ctrl:1
	v_add_f32_dpp v42, v42, v42 row_half_mirror row_mask:0xf bank_mask:0xf bound_ctrl:1
	v_add_f32_dpp v44, v44, v44 row_half_mirror row_mask:0xf bank_mask:0xf bound_ctrl:1
	v_add_f32_dpp v46, v46, v46 row_half_mirror row_mask:0xf bank_mask:0xf bound_ctrl:1
	v_pk_fma_f32 v[8:9], v[8:9], v[212:213], v[88:89]
	v_pk_fma_f32 v[0:1], v[0:1], v[212:213], v[90:91]
	v_pk_fma_f32 v[10:11], v[10:11], v[214:215], v[92:93]
	v_pk_fma_f32 v[2:3], v[2:3], v[214:215], v[94:95]
	v_pk_fma_f32 v[12:13], v[224:225], v[40:41], v[12:13] op_sel_hi:[1,0,1] neg_lo:[0,1,0] neg_hi:[0,1,0]
	v_pk_fma_f32 v[4:5], v[224:225], v[42:43], v[4:5] op_sel_hi:[1,0,1] neg_lo:[0,1,0] neg_hi:[0,1,0]
	v_pk_fma_f32 v[14:15], v[226:227], v[40:41], v[14:15] op_sel_hi:[1,0,1] neg_lo:[0,1,0] neg_hi:[0,1,0]
	v_pk_fma_f32 v[6:7], v[226:227], v[42:43], v[6:7] op_sel_hi:[1,0,1] neg_lo:[0,1,0] neg_hi:[0,1,0]
	v_pk_fma_f32 v[8:9], v[228:229], v[40:41], v[8:9] op_sel_hi:[1,0,1] neg_lo:[0,1,0] neg_hi:[0,1,0]
	v_pk_fma_f32 v[0:1], v[228:229], v[42:43], v[0:1] op_sel_hi:[1,0,1] neg_lo:[0,1,0] neg_hi:[0,1,0]
	v_pk_fma_f32 v[10:11], v[230:231], v[40:41], v[10:11] op_sel_hi:[1,0,1] neg_lo:[0,1,0] neg_hi:[0,1,0]
	v_pk_fma_f32 v[2:3], v[230:231], v[42:43], v[2:3] op_sel_hi:[1,0,1] neg_lo:[0,1,0] neg_hi:[0,1,0]
	s_and_saveexec_b64 s[42:43], s[6:7]
	ds_write2_b32 v168, v44, v46 offset0:64 offset1:72
	s_mov_b64 exec, s[42:43]
	ds_read_b128 v[240:243], v166 offset:20224
	ds_read_b128 v[244:247], v166 offset:20240
	s_waitcnt lgkmcnt(3)
; #define LAS __attribute__((address_space(3)))
; template <int CTRL> __device__ __forceinline__ float dpp_f(float x) { return __builtin_bit_cast(float, __builtin_amdgcn_mov_dpp(__builtin_bit_cast(int, x), CTRL, 0xf, 0xf, true)); }
; __device__ __forceinline__ float red8(float d) { d += dpp_f<0xB1>(d); d += dpp_f<0x4E>(d); d += dpp_f<0x141>(d); return d; }
; __device__ __forceinline__ void upd8(V8& S, const V8& w, const V8& b, const V8& k, float sa, float vv) {
;     const f32x2 sa2 = {sa, sa}, vv2 = {vv, vv};
; #pragma unroll
;     for (int i = 0; i < 4; ++i) { f32x2 t = vv2 * k.p[i]; t = sa2 * b.p[i] + t; S.p[i] = S.p[i] * w.p[i] + t; }
; template <int MODE>
; __device__ __forceinline__ void scan_pair(LAS unsigned char* lds, CArgsP a, const ScanUnit u, int nch) {
;     ...
;         for (int t = 0; t < 16; ++t) {
;             const LAS float* p = cb + t * 64 + 8 * ks;
;             const V8 w = ld8(p), kk = ld8(p + 1024), bb = ld8(p + 2048), kv = ld8(p + 3072);
;             const float va = cb[(5 * 16 + t) * 64 + vr0], vb = cb[(5 * 16 + t) * 64 + vr1];
;             float da = dot8(Sa, kk), db = dot8(Sb, kk);
;             da = red8(da); db = red8(db);
;             upd8(Sa, w, bb, kv, -da, va); upd8(Sb, w, bb, kv, -db, vb);
;             if (MODE == 1) {
;                 float pa = dot8(Pa, kk), pb = dot8(Pb, kk);
;                 pa = red8(pa); pb = red8(pb);
;                 updp8(Pa, w, bb, -pa); updp8(Pb, w, bb, -pb);
;             } else {
;                 const V8 rr = ld8(p + 4096);
;                 float ya = dot8(Sa, rr), yb = dot8(Sb, rr);
;                 ya = red8(ya); yb = red8(yb);
;                 if (ks == 0) { Y[t * 64 + vr0] = ya; Y[t * 64 + vr1] = yb; }
;             }
	v_pk_mul_f32 v[40:41], v[12:13], v[112:113]
	v_pk_mul_f32 v[42:43], v[4:5], v[112:113]
	v_pk_mul_f32 v[44:45], v[12:13], v[136:137]
	v_pk_mul_f32 v[46:47], v[4:5], v[136:137]
	v_pk_fma_f32 v[40:41], v[14:15], v[114:115], v[40:41]
	v_pk_fma_f32 v[42:43], v[6:7], v[114:115], v[42:43]
	v_pk_fma_f32 v[44:45], v[14:15], v[138:139], v[44:45]
	v_pk_fma_f32 v[46:47], v[6:7], v[138:139], v[46:47]
	v_pk_fma_f32 v[40:41], v[8:9], v[116:117], v[40:41]
	v_pk_fma_f32 v[42:43], v[0:1], v[116:117], v[42:43]
	v_pk_fma_f32 v[44:45], v[8:9], v[140:141], v[44:45]
	v_pk_fma_f32 v[46:47], v[0:1], v[140:141], v[46:47]
	v_pk_fma_f32 v[40:41], v[10:11], v[118:119], v[40:41]
	v_pk_fma_f32 v[42:43], v[2:3], v[118:119], v[42:43]
	v_pk_fma_f32 v[44:45], v[10:11], v[142:143], v[44:45]
	v_pk_fma_f32 v[46:47], v[2:3], v[142:143], v[46:47]
	v_add_f32_e32 v40, v40, v41
	v_add_f32_e32 v42, v42, v43
	v_add_f32_e32 v44, v44, v45
	v_add_f32_e32 v46, v46, v47
	v_pk_mul_f32 v[88:89], v[128:129], v[98:99] op_sel_hi:[1,0]
	v_pk_mul_f32 v[90:91], v[128:129], v[98:99] op_sel:[0,1] op_sel_hi:[1,1]
	v_pk_mul_f32 v[92:93], v[130:131], v[98:99] op_sel_hi:[1,0]
	v_pk_mul_f32 v[94:95], v[130:131], v[98:99] op_sel:[0,1] op_sel_hi:[1,1]
	v_add_f32_dpp v40, v40, v40 quad_perm:[1,0,3,2] row_mask:0xf bank_mask:0xf bound_ctrl:1
	v_add_f32_dpp v42, v42, v42 quad_perm:[1,0,3,2] row_mask:0xf bank_mask:0xf bound_ctrl:1
	v_add_f32_dpp v44, v44, v44 quad_perm:[1,0,3,2] row_mask:0xf bank_mask:0xf bound_ctrl:1
	v_add_f32_dpp v46, v46, v46 quad_perm:[1,0,3,2] row_mask:0xf bank_mask:0xf bound_ctrl:1
	v_pk_fma_f32 v[12:13], v[12:13], v[104:105], v[88:89]
	v_pk_fma_f32 v[4:5], v[4:5], v[104:105], v[90:91]
	v_pk_fma_f32 v[14:15], v[14:15], v[106:107], v[92:93]
	v_pk_fma_f32 v[6:7], v[6:7], v[106:107], v[94:95]
	v_add_f32_dpp v40, v40, v40 quad_perm:[2,3,0,1] row_mask:0xf bank_mask:0xf bound_ctrl:1
	v_add_f32_dpp v42, v42, v42 quad_perm:[2,3,0,1] row_mask:0xf bank_mask:0xf bound_ctrl:1
	v_add_f32_dpp v44, v44, v44 quad_perm:[2,3,0,1] row_mask:0xf bank_mask:0xf bound_ctrl:1
	v_add_f32_dpp v46, v46, v46 quad_perm:[2,3,0,1] row_mask:0xf bank_mask:0xf bound_ctrl:1
	v_pk_mul_f32 v[88:89], v[132:133], v[98:99] op_sel_hi:[1,0]
	v_pk_mul_f32 v[90:91], v[132:133], v[98:99] op_sel:[0,1] op_sel_hi:[1,1]
	v_pk_mul_f32 v[92:93], v[134:135], v[98:99] op_sel_hi:[1,0]
	v_pk_mul_f32 v[94:95], v[134:135], v[98:99] op_sel:[0,1] op_sel_hi:[1,1]
	v_add_f32_dpp v40, v40, v40 row_half_mirror row_mask:0xf bank_mask:0xf bound_ctrl:1
	v_add_f32_dpp v42, v42, v42 row_half_mirror row_mask:0xf bank_mask:0xf bound_ctrl:1
	v_add_f32_dpp v44, v44, v44 row_half_mirror row_mask:0xf bank_mask:0xf bound_ctrl:1
	v_add_f32_dpp v46, v46, v46 row_half_mirror row_mask:0xf bank_mask:0xf bound_ctrl:1
	v_pk_fma_f32 v[8:9], v[8:9], v[108:109], v[88:89]
	v_pk_fma_f32 v[0:1], v[0:1], v[108:109], v[90:91]
	v_pk_fma_f32 v[10:11], v[10:11], v[110:111], v[92:93]
	v_pk_fma_f32 v[2:3], v[2:3], v[110:111], v[94:95]
	v_pk_fma_f32 v[12:13], v[120:121], v[40:41], v[12:13] op_sel_hi:[1,0,1] neg_lo:[0,1,0] neg_hi:[0,1,0]
	v_pk_fma_f32 v[4:5], v[120:121], v[42:43], v[4:5] op_sel_hi:[1,0,1] neg_lo:[0,1,0] neg_hi:[0,1,0]
	v_pk_fma_f32 v[14:15], v[122:123], v[40:41], v[14:15] op_sel_hi:[1,0,1] neg_lo:[0,1,0] neg_hi:[0,1,0]
	v_pk_fma_f32 v[6:7], v[122:123], v[42:43], v[6:7] op_sel_hi:[1,0,1] neg_lo:[0,1,0] neg_hi:[0,1,0]
	v_pk_fma_f32 v[8:9], v[124:125], v[40:41], v[8:9] op_sel_hi:[1,0,1] neg_lo:[0,1,0] neg_hi:[0,1,0]
	v_pk_fma_f32 v[0:1], v[124:125], v[42:43], v[0:1] op_sel_hi:[1,0,1] neg_lo:[0,1,0] neg_hi:[0,1,0]
	v_pk_fma_f32 v[10:11], v[126:127], v[40:41], v[10:11] op_sel_hi:[1,0,1] neg_lo:[0,1,0] neg_hi:[0,1,0]
	v_pk_fma_f32 v[2:3], v[126:127], v[42:43], v[2:3] op_sel_hi:[1,0,1] neg_lo:[0,1,0] neg_hi:[0,1,0]
	s_and_saveexec_b64 s[42:43], s[6:7]
	ds_write2_b32 v168, v44, v46 offset0:128 offset1:136
	s_mov_b64 exec, s[42:43]
	s_waitcnt lgkmcnt(1)
	v_pk_mul_f32 v[44:45], v[12:13], v[240:241]
	v_pk_mul_f32 v[46:47], v[4:5], v[240:241]
	v_pk_fma_f32 v[44:45], v[14:15], v[242:243], v[44:45]
	v_pk_fma_f32 v[46:47], v[6:7], v[242:243], v[46:47]
	v_pk_fma_f32 v[44:45], v[8:9], v[244:245], v[44:45]
	v_pk_fma_f32 v[46:47], v[0:1], v[244:245], v[46:47]
	v_pk_fma_f32 v[44:45], v[10:11], v[246:247], v[44:45]
	v_pk_fma_f32 v[46:47], v[2:3], v[246:247], v[46:47]
	v_add_f32_e32 v44, v44, v45
	v_add_f32_e32 v46, v46, v47
	s_nop 0
	v_add_f32_dpp v44, v44, v44 quad_perm:[1,0,3,2] row_mask:0xf bank_mask:0xf bound_ctrl:1
	v_add_f32_dpp v46, v46, v46 quad_perm:[1,0,3,2] row_mask:0xf bank_mask:0xf bound_ctrl:1
	s_nop 1
	v_add_f32_dpp v44, v44, v44 quad_perm:[2,3,0,1] row_mask:0xf bank_mask:0xf bound_ctrl:1
	v_add_f32_dpp v46, v46, v46 quad_perm:[2,3,0,1] row_mask:0xf bank_mask:0xf bound_ctrl:1
	s_nop 1
	v_add_f32_dpp v44, v44, v44 row_half_mirror row_mask:0xf bank_mask:0xf bound_ctrl:1
	v_add_f32_dpp v46, v46, v46 row_half_mirror row_mask:0xf bank_mask:0xf bound_ctrl:1
	s_nop 1
	s_and_saveexec_b64 s[42:43], s[6:7]
	ds_write2_b32 v168, v44, v46 offset0:192 offset1:200
	s_mov_b64 exec, s[42:43]
